# v81_kloop_backedge_bookkeeping_before_closing_barrier
# baseline (speedup 1.0000x reference)
; #define PG8_STAGE(bufoff, goff, voff) do { _Pragma("unroll") for (int _i = 0; _i < 2; ++_i) { unsigned _vo = (voff)[_i] + (goff); asm volatile("" : "+v"(_vo)); \
;         __builtin_amdgcn_global_load_lds((const unsigned*)(base_##voff + _vo), (LAS unsigned*)(lds + (bufoff) + ldsw + _i * 8192), 16, 0, 0); } } while (0)
; #define PG8_WAIT_V(n) asm volatile("s_waitcnt vmcnt(" #n ")" ::: "memory")
; #define PG8_BAR __builtin_amdgcn_s_barrier()
;     ...
;     Unit cur, nxt; int ui = 0;
;     if (!S.next(0, cur)) return;
;     f32x4 acc[2][2][4][2];
; #pragma unroll
;     for (int a = 0; a < 2; ++a)
; #pragma unroll
;         for (int b = 0; b < 2; ++b)
; #pragma unroll
;             for (int m = 0; m < 4; ++m)
; #pragma unroll
;                 for (int n = 0; n < 2; ++n) acc[a][b][m][n] = (f32x4){0.f, 0.f, 0.f, 0.f};
;     bf16x8 At[4][2], B0[2][2], B1[2][2];
;     unsigned cA = (unsigned)cur.pm * tstepA, cB = (unsigned)cur.pn * tstepB;
;     PG8_STAGE(PG8_SB(0, 0), cB, voffB); PG8_STAGE(PG8_SB(0, 1), cB + hstepB, voffB); PG8_STAGE(PG8_SA(0, 0), cA + PG8_KOFFA(0), voffA); PG8_STAGE(PG8_SA(0, 1), cA + hstepA + PG8_KOFFA(0), voffA);
;     if (wr == 1) PG8_BAR;
;     PG8_WAIT_V(2); PG8_BAR;
;     PG8_STAGE(PG8_SB(1, 0), cB + kstep, voffB); PG8_STAGE(PG8_SA(1, 0), cA + PG8_KOFFA(1), voffA); PG8_STAGE(PG8_SB(1, 1), cB + hstepB + kstep, voffB);
;     PG8_WAIT_V(6); PG8_BAR;
;     for (;;) {
;         const bool has_next = S.next(ui + 1, nxt);
;         const unsigned nA = has_next ? (unsigned)nxt.pm * tstepA : cA, nB = has_next ? (unsigned)nxt.pn * tstepB : cB;
.LBB0_188:
	ds_read_b128 v[152:155], v147
	ds_read_b128 v[156:159], v147 offset:1024
	ds_read_b128 v[160:163], v147 offset:2048
	ds_read_b128 v[164:167], v147 offset:3072
	ds_read_b128 v[168:171], v149
	ds_read_b128 v[172:175], v149 offset:1024
	ds_read_b128 v[176:179], v149 offset:2048
	ds_read_b128 v[180:183], v149 offset:3072
	s_cmp_eq_u32 s8, 12
	s_cselect_b32 s49, s0, s3
	s_cselect_b32 s48, s1, s2
	s_or_b32 s9, s49, 0x80
	v_mov_b32_e32 v136, v135
	ds_read_b128 v[188:191], v150
	ds_read_b128 v[192:195], v150 offset:1024
	ds_read_b128 v[196:199], v150 offset:2048
	ds_read_b128 v[200:203], v150 offset:3072
	ds_read_b128 v[204:207], v150 offset:4096
	ds_read_b128 v[208:211], v150 offset:5120
	ds_read_b128 v[212:215], v150 offset:6144
	ds_read_b128 v[216:219], v150 offset:7168
	s_add_i32 m0, s25, 0xc000
	s_nop 0
	global_load_lds_dwordx4 v136, s[10:11]
	v_mov_b32_e32 v136, v134
	s_add_i32 m0, s25, 0xe000
	s_nop 0
	global_load_lds_dwordx4 v136, s[10:11]
	s_waitcnt vmcnt(8)
	s_waitcnt lgkmcnt(0)
	s_barrier
	s_setprio 1
	s_waitcnt lgkmcnt(0)
	v_mfma_f32_16x16x32_bf16 v[124:127], v[152:155], v[188:191], v[124:127]
	v_mfma_f32_16x16x32_bf16 v[120:123], v[160:163], v[188:191], v[120:123]
	v_mfma_f32_16x16x32_bf16 v[108:111], v[152:155], v[196:199], v[108:111]
	v_mfma_f32_16x16x32_bf16 v[104:107], v[160:163], v[196:199], v[104:107]
	v_mfma_f32_16x16x32_bf16 v[92:95], v[152:155], v[204:207], v[92:95]
	v_mfma_f32_16x16x32_bf16 v[88:91], v[160:163], v[204:207], v[88:91]
	v_mfma_f32_16x16x32_bf16 v[76:79], v[152:155], v[212:215], v[76:79]
	v_mfma_f32_16x16x32_bf16 v[72:75], v[160:163], v[212:215], v[72:75]
	v_mfma_f32_16x16x32_bf16 v[124:127], v[156:159], v[192:195], v[124:127]
	v_mfma_f32_16x16x32_bf16 v[120:123], v[164:167], v[192:195], v[120:123]
	v_mfma_f32_16x16x32_bf16 v[108:111], v[156:159], v[200:203], v[108:111]
	v_mfma_f32_16x16x32_bf16 v[104:107], v[164:167], v[200:203], v[104:107]
	v_mfma_f32_16x16x32_bf16 v[92:95], v[156:159], v[208:211], v[92:95]
	v_mfma_f32_16x16x32_bf16 v[88:91], v[164:167], v[208:211], v[88:91]
	v_mfma_f32_16x16x32_bf16 v[76:79], v[156:159], v[216:219], v[76:79]
	v_mfma_f32_16x16x32_bf16 v[72:75], v[164:167], v[216:219], v[72:75]
	s_setprio 0
	s_setprio 1
	v_mfma_f32_16x16x32_bf16 v[116:119], v[168:171], v[188:191], v[116:119]
	v_mfma_f32_16x16x32_bf16 v[112:115], v[176:179], v[188:191], v[112:115]
	v_mfma_f32_16x16x32_bf16 v[100:103], v[168:171], v[196:199], v[100:103]
	v_mfma_f32_16x16x32_bf16 v[96:99], v[176:179], v[196:199], v[96:99]
	v_mfma_f32_16x16x32_bf16 v[84:87], v[168:171], v[204:207], v[84:87]
	v_mfma_f32_16x16x32_bf16 v[80:83], v[176:179], v[204:207], v[80:83]
	v_mfma_f32_16x16x32_bf16 v[68:71], v[168:171], v[212:215], v[68:71]
	v_mfma_f32_16x16x32_bf16 v[64:67], v[176:179], v[212:215], v[64:67]
	v_mfma_f32_16x16x32_bf16 v[116:119], v[172:175], v[192:195], v[116:119]
	v_mfma_f32_16x16x32_bf16 v[112:115], v[180:183], v[192:195], v[112:115]
	v_mfma_f32_16x16x32_bf16 v[100:103], v[172:175], v[200:203], v[100:103]
	v_mfma_f32_16x16x32_bf16 v[96:99], v[180:183], v[200:203], v[96:99]
	v_mfma_f32_16x16x32_bf16 v[84:87], v[172:175], v[208:211], v[84:87]
	v_mfma_f32_16x16x32_bf16 v[80:83], v[180:183], v[208:211], v[80:83]
	v_mfma_f32_16x16x32_bf16 v[68:71], v[172:175], v[216:219], v[68:71]
	v_mfma_f32_16x16x32_bf16 v[64:67], v[180:183], v[216:219], v[64:67]
	s_setprio 0
	s_barrier
	v_add_u32_e32 v136, s48, v139
	s_add_i32 s50, s41, s24
	ds_read_b128 v[188:191], v150 offset:16384
	ds_read_b128 v[192:195], v150 offset:17408
	ds_read_b128 v[196:199], v150 offset:18432
	ds_read_b128 v[200:203], v150 offset:19456
	ds_read_b128 v[204:207], v150 offset:20480
	ds_read_b128 v[208:211], v150 offset:21504
	ds_read_b128 v[212:215], v150 offset:22528
	ds_read_b128 v[216:219], v150 offset:23552
	s_mov_b32 m0, s50
	s_add_i32 s51, s42, s24
	global_load_lds_dwordx4 v136, s[12:13]
	v_add_u32_e32 v136, s48, v141
	s_add_i32 m0, s50, 0x2000
	s_add_i32 s50, s48, 0x40000
	global_load_lds_dwordx4 v136, s[12:13]
	v_add_u32_e32 v136, s50, v139
	s_mov_b32 m0, s51
	s_nop 0
	global_load_lds_dwordx4 v136, s[12:13]
	v_add_u32_e32 v136, s50, v141
	s_add_i32 m0, s51, 0x2000
	s_nop 0
	global_load_lds_dwordx4 v136, s[12:13]
	v_add_u32_e32 v136, s49, v138
	s_mov_b32 m0, s25
	s_nop 0
	global_load_lds_dwordx4 v136, s[10:11]
	v_add_u32_e32 v136, s49, v140
	s_mov_b32 m0, s26
	s_nop 0
	global_load_lds_dwordx4 v136, s[10:11]
	s_waitcnt vmcnt(8)
	s_waitcnt lgkmcnt(0)
	s_barrier
	s_setprio 1
	s_waitcnt lgkmcnt(0)
	v_mfma_f32_16x16x32_bf16 v[60:63], v[152:155], v[188:191], v[60:63]
	v_mfma_f32_16x16x32_bf16 v[56:59], v[160:163], v[188:191], v[56:59]
	v_mfma_f32_16x16x32_bf16 v[44:47], v[152:155], v[196:199], v[44:47]
	v_mfma_f32_16x16x32_bf16 v[40:43], v[160:163], v[196:199], v[40:43]
	v_mfma_f32_16x16x32_bf16 v[28:31], v[152:155], v[204:207], v[28:31]
	v_mfma_f32_16x16x32_bf16 v[24:27], v[160:163], v[204:207], v[24:27]
	v_mfma_f32_16x16x32_bf16 v[12:15], v[152:155], v[212:215], v[12:15]
	v_mfma_f32_16x16x32_bf16 v[8:11], v[160:163], v[212:215], v[8:11]
	v_mfma_f32_16x16x32_bf16 v[60:63], v[156:159], v[192:195], v[60:63]
	v_mfma_f32_16x16x32_bf16 v[56:59], v[164:167], v[192:195], v[56:59]
	v_mfma_f32_16x16x32_bf16 v[44:47], v[156:159], v[200:203], v[44:47]
	v_mfma_f32_16x16x32_bf16 v[40:43], v[164:167], v[200:203], v[40:43]
	v_mfma_f32_16x16x32_bf16 v[28:31], v[156:159], v[208:211], v[28:31]
	v_mfma_f32_16x16x32_bf16 v[24:27], v[164:167], v[208:211], v[24:27]
	v_mfma_f32_16x16x32_bf16 v[12:15], v[156:159], v[216:219], v[12:15]
	v_mfma_f32_16x16x32_bf16 v[8:11], v[164:167], v[216:219], v[8:11]
	s_setprio 0
	s_setprio 1
	v_mfma_f32_16x16x32_bf16 v[52:55], v[168:171], v[188:191], v[52:55]
	v_mfma_f32_16x16x32_bf16 v[48:51], v[176:179], v[188:191], v[48:51]
	v_mfma_f32_16x16x32_bf16 v[36:39], v[168:171], v[196:199], v[36:39]
	v_mfma_f32_16x16x32_bf16 v[32:35], v[176:179], v[196:199], v[32:35]
	v_mfma_f32_16x16x32_bf16 v[20:23], v[168:171], v[204:207], v[20:23]
	v_mfma_f32_16x16x32_bf16 v[16:19], v[176:179], v[204:207], v[16:19]
	v_mfma_f32_16x16x32_bf16 v[4:7], v[168:171], v[212:215], v[4:7]
	v_mfma_f32_16x16x32_bf16 v[0:3], v[176:179], v[212:215], v[0:3]
	v_mfma_f32_16x16x32_bf16 v[52:55], v[172:175], v[192:195], v[52:55]
	v_mfma_f32_16x16x32_bf16 v[48:51], v[180:183], v[192:195], v[48:51]
	v_mfma_f32_16x16x32_bf16 v[36:39], v[172:175], v[200:203], v[36:39]
	v_mfma_f32_16x16x32_bf16 v[32:35], v[180:183], v[200:203], v[32:35]
	v_mfma_f32_16x16x32_bf16 v[20:23], v[172:175], v[208:211], v[20:23]
	v_mfma_f32_16x16x32_bf16 v[16:19], v[180:183], v[208:211], v[16:19]
	v_mfma_f32_16x16x32_bf16 v[4:7], v[172:175], v[216:219], v[4:7]
	v_mfma_f32_16x16x32_bf16 v[0:3], v[180:183], v[216:219], v[0:3]
	s_setprio 0
	s_barrier
;     ...
;         if constexpr (Epi::MIDHOOK) {
;             for (int t = 0; t < 4; t += 2) PG8_ITER(t);
;             E.mid(acc, cur, wr, wc, fr, fq);
;             for (int t = 4; t < nt; t += 2) PG8_ITER(t);
;         } else {
;             for (int t = 0; t < nt; t += 2) PG8_ITER(t);
	s_add_i32 s50, 0, 0x18000
	v_add_u32_e32 v136, s50, v143
	s_add_i32 s51, 0, 0x1c000
	ds_read_b128 v[152:155], v136
	ds_read_b128 v[156:159], v136 offset:1024
	ds_read_b128 v[160:163], v136 offset:2048
	ds_read_b128 v[164:167], v136 offset:3072
	v_add_u32_e32 v136, s51, v143
	ds_read_b128 v[168:171], v136
	ds_read_b128 v[172:175], v136 offset:1024
	ds_read_b128 v[176:179], v136 offset:2048
	ds_read_b128 v[180:183], v136 offset:3072
	s_add_i32 s49, s49, 0x40000
	v_add_u32_e32 v136, s49, v138
	s_mov_b32 m0, s27
	ds_read_b128 v[188:191], v150 offset:32768
	ds_read_b128 v[192:195], v150 offset:33792
	ds_read_b128 v[196:199], v150 offset:34816
	ds_read_b128 v[200:203], v150 offset:35840
	ds_read_b128 v[204:207], v150 offset:36864
	ds_read_b128 v[208:211], v150 offset:37888
	ds_read_b128 v[212:215], v150 offset:38912
	ds_read_b128 v[216:219], v150 offset:39936
	s_nop 0
	global_load_lds_dwordx4 v136, s[10:11]
	v_add_u32_e32 v136, s49, v140
	s_mov_b32 m0, s28
	s_nop 0
	global_load_lds_dwordx4 v136, s[10:11]
	s_waitcnt vmcnt(8)
	s_waitcnt lgkmcnt(0)
	s_barrier
	s_setprio 1
	s_waitcnt lgkmcnt(0)
	v_mfma_f32_16x16x32_bf16 v[124:127], v[152:155], v[188:191], v[124:127]
	v_mfma_f32_16x16x32_bf16 v[120:123], v[160:163], v[188:191], v[120:123]
	v_mfma_f32_16x16x32_bf16 v[108:111], v[152:155], v[196:199], v[108:111]
	v_mfma_f32_16x16x32_bf16 v[104:107], v[160:163], v[196:199], v[104:107]
	v_mfma_f32_16x16x32_bf16 v[92:95], v[152:155], v[204:207], v[92:95]
	v_mfma_f32_16x16x32_bf16 v[88:91], v[160:163], v[204:207], v[88:91]
	v_mfma_f32_16x16x32_bf16 v[76:79], v[152:155], v[212:215], v[76:79]
	v_mfma_f32_16x16x32_bf16 v[72:75], v[160:163], v[212:215], v[72:75]
	v_mfma_f32_16x16x32_bf16 v[124:127], v[156:159], v[192:195], v[124:127]
	v_mfma_f32_16x16x32_bf16 v[120:123], v[164:167], v[192:195], v[120:123]
	v_mfma_f32_16x16x32_bf16 v[108:111], v[156:159], v[200:203], v[108:111]
	v_mfma_f32_16x16x32_bf16 v[104:107], v[164:167], v[200:203], v[104:107]
	v_mfma_f32_16x16x32_bf16 v[92:95], v[156:159], v[208:211], v[92:95]
	v_mfma_f32_16x16x32_bf16 v[88:91], v[164:167], v[208:211], v[88:91]
	v_mfma_f32_16x16x32_bf16 v[76:79], v[156:159], v[216:219], v[76:79]
	v_mfma_f32_16x16x32_bf16 v[72:75], v[164:167], v[216:219], v[72:75]
	s_setprio 0
	s_setprio 1
	v_mfma_f32_16x16x32_bf16 v[116:119], v[168:171], v[188:191], v[116:119]
	v_mfma_f32_16x16x32_bf16 v[112:115], v[176:179], v[188:191], v[112:115]
	v_mfma_f32_16x16x32_bf16 v[100:103], v[168:171], v[196:199], v[100:103]
	v_mfma_f32_16x16x32_bf16 v[96:99], v[176:179], v[196:199], v[96:99]
	v_mfma_f32_16x16x32_bf16 v[84:87], v[168:171], v[204:207], v[84:87]
	v_mfma_f32_16x16x32_bf16 v[80:83], v[176:179], v[204:207], v[80:83]
	v_mfma_f32_16x16x32_bf16 v[68:71], v[168:171], v[212:215], v[68:71]
	v_mfma_f32_16x16x32_bf16 v[64:67], v[176:179], v[212:215], v[64:67]
	v_mfma_f32_16x16x32_bf16 v[116:119], v[172:175], v[192:195], v[116:119]
	v_mfma_f32_16x16x32_bf16 v[112:115], v[180:183], v[192:195], v[112:115]
	v_mfma_f32_16x16x32_bf16 v[100:103], v[172:175], v[200:203], v[100:103]
	v_mfma_f32_16x16x32_bf16 v[96:99], v[180:183], v[200:203], v[96:99]
	v_mfma_f32_16x16x32_bf16 v[84:87], v[172:175], v[208:211], v[84:87]
	v_mfma_f32_16x16x32_bf16 v[80:83], v[180:183], v[208:211], v[80:83]
	v_mfma_f32_16x16x32_bf16 v[68:71], v[172:175], v[216:219], v[68:71]
	v_mfma_f32_16x16x32_bf16 v[64:67], v[180:183], v[216:219], v[64:67]
	s_setprio 0
	s_barrier
	s_or_b32 s49, s48, 0x80
	v_add_u32_e32 v136, s49, v139
	s_add_i32 s50, s50, s24
	ds_read_b128 v[188:191], v150 offset:49152
	ds_read_b128 v[192:195], v150 offset:50176
	ds_read_b128 v[196:199], v150 offset:51200
	ds_read_b128 v[200:203], v150 offset:52224
	ds_read_b128 v[204:207], v150 offset:53248
	ds_read_b128 v[208:211], v150 offset:54272
	ds_read_b128 v[212:215], v150 offset:55296
	ds_read_b128 v[216:219], v150 offset:56320
	s_mov_b32 m0, s50
	s_add_i32 s48, s48, 0x40080
	global_load_lds_dwordx4 v136, s[12:13]
	v_add_u32_e32 v136, s49, v141
	s_add_i32 m0, s50, 0x2000
	s_add_i32 s49, s51, s24
	global_load_lds_dwordx4 v136, s[12:13]
	v_add_u32_e32 v136, s48, v139
	s_mov_b32 m0, s49
	s_nop 0
	global_load_lds_dwordx4 v136, s[12:13]
	v_add_u32_e32 v136, s48, v141
	s_add_i32 m0, s49, 0x2000
	s_nop 0
	global_load_lds_dwordx4 v136, s[12:13]
	v_add_u32_e32 v136, s9, v138
	s_mov_b32 m0, s30
	s_nop 0
	global_load_lds_dwordx4 v136, s[10:11]
	v_add_u32_e32 v136, s9, v140
	s_mov_b32 m0, s31
	s_nop 0
	global_load_lds_dwordx4 v136, s[10:11]
	s_waitcnt vmcnt(8)
	s_waitcnt lgkmcnt(0)
	s_barrier
	s_setprio 1
	s_waitcnt lgkmcnt(0)
	v_mfma_f32_16x16x32_bf16 v[60:63], v[152:155], v[188:191], v[60:63]
	v_mfma_f32_16x16x32_bf16 v[56:59], v[160:163], v[188:191], v[56:59]
	v_mfma_f32_16x16x32_bf16 v[44:47], v[152:155], v[196:199], v[44:47]
	v_mfma_f32_16x16x32_bf16 v[40:43], v[160:163], v[196:199], v[40:43]
	v_mfma_f32_16x16x32_bf16 v[28:31], v[152:155], v[204:207], v[28:31]
	v_mfma_f32_16x16x32_bf16 v[24:27], v[160:163], v[204:207], v[24:27]
	v_mfma_f32_16x16x32_bf16 v[12:15], v[152:155], v[212:215], v[12:15]
	v_mfma_f32_16x16x32_bf16 v[8:11], v[160:163], v[212:215], v[8:11]
	v_mfma_f32_16x16x32_bf16 v[60:63], v[156:159], v[192:195], v[60:63]
	v_mfma_f32_16x16x32_bf16 v[56:59], v[164:167], v[192:195], v[56:59]
	v_mfma_f32_16x16x32_bf16 v[44:47], v[156:159], v[200:203], v[44:47]
	v_mfma_f32_16x16x32_bf16 v[40:43], v[164:167], v[200:203], v[40:43]
	v_mfma_f32_16x16x32_bf16 v[28:31], v[156:159], v[208:211], v[28:31]
	v_mfma_f32_16x16x32_bf16 v[24:27], v[164:167], v[208:211], v[24:27]
	v_mfma_f32_16x16x32_bf16 v[12:15], v[156:159], v[216:219], v[12:15]
	v_mfma_f32_16x16x32_bf16 v[8:11], v[164:167], v[216:219], v[8:11]
	s_setprio 0
	s_setprio 1
	v_mfma_f32_16x16x32_bf16 v[52:55], v[168:171], v[188:191], v[52:55]
	v_mfma_f32_16x16x32_bf16 v[48:51], v[176:179], v[188:191], v[48:51]
	v_mfma_f32_16x16x32_bf16 v[36:39], v[168:171], v[196:199], v[36:39]
	v_mfma_f32_16x16x32_bf16 v[32:35], v[176:179], v[196:199], v[32:35]
	v_mfma_f32_16x16x32_bf16 v[20:23], v[168:171], v[204:207], v[20:23]
	v_mfma_f32_16x16x32_bf16 v[16:19], v[176:179], v[204:207], v[16:19]
	v_mfma_f32_16x16x32_bf16 v[4:7], v[168:171], v[212:215], v[4:7]
	v_mfma_f32_16x16x32_bf16 v[0:3], v[176:179], v[212:215], v[0:3]
	v_mfma_f32_16x16x32_bf16 v[52:55], v[172:175], v[192:195], v[52:55]
	v_mfma_f32_16x16x32_bf16 v[48:51], v[180:183], v[192:195], v[48:51]
	v_mfma_f32_16x16x32_bf16 v[36:39], v[172:175], v[200:203], v[36:39]
	v_mfma_f32_16x16x32_bf16 v[32:35], v[180:183], v[200:203], v[32:35]
	v_mfma_f32_16x16x32_bf16 v[20:23], v[172:175], v[208:211], v[20:23]
	v_mfma_f32_16x16x32_bf16 v[16:19], v[180:183], v[208:211], v[16:19]
	v_mfma_f32_16x16x32_bf16 v[4:7], v[172:175], v[216:219], v[4:7]
	v_mfma_f32_16x16x32_bf16 v[0:3], v[180:183], v[216:219], v[0:3]
	s_setprio 0
	s_add_i32 s8, s8, 2
	s_addk_i32 s2, 0x100
	s_addk_i32 s3, 0x100
	v_add_u32_e32 v134, 0x100, v134
	s_cmp_gt_u32 s8, 13
	v_add_u32_e32 v135, 0x100, v135
	s_barrier
	s_cbranch_scc0 .LBB0_188
	s_and_b64 vcc, exec, s[18:19]
	s_cbranch_vccz .LBB0_191
	s_barrier

; #define PG8_STAGE(bufoff, goff, voff) do { _Pragma("unroll") for (int _i = 0; _i < 2; ++_i) { unsigned _vo = (voff)[_i] + (goff); asm volatile("" : "+v"(_vo)); \
;         __builtin_amdgcn_global_load_lds((const unsigned*)(base_##voff + _vo), (LAS unsigned*)(lds + (bufoff) + ldsw + _i * 8192), 16, 0, 0); } } while (0)
; #define PG8_WAIT_V(n) asm volatile("s_waitcnt vmcnt(" #n ")" ::: "memory")
; #define PG8_BAR __builtin_amdgcn_s_barrier()
;     ...
;     Unit cur, nxt; int ui = 0;
;     if (!S.next(0, cur)) return;
;     f32x4 acc[2][2][4][2];
; #pragma unroll
;     for (int a = 0; a < 2; ++a)
; #pragma unroll
;         for (int b = 0; b < 2; ++b)
; #pragma unroll
;             for (int m = 0; m < 4; ++m)
; #pragma unroll
;                 for (int n = 0; n < 2; ++n) acc[a][b][m][n] = (f32x4){0.f, 0.f, 0.f, 0.f};
;     bf16x8 At[4][2], B0[2][2], B1[2][2];
;     unsigned cA = (unsigned)cur.pm * tstepA, cB = (unsigned)cur.pn * tstepB;
;     PG8_STAGE(PG8_SB(0, 0), cB, voffB); PG8_STAGE(PG8_SB(0, 1), cB + hstepB, voffB); PG8_STAGE(PG8_SA(0, 0), cA + PG8_KOFFA(0), voffA); PG8_STAGE(PG8_SA(0, 1), cA + hstepA + PG8_KOFFA(0), voffA);
;     if (wr == 1) PG8_BAR;
;     PG8_WAIT_V(2); PG8_BAR;
;     PG8_STAGE(PG8_SB(1, 0), cB + kstep, voffB); PG8_STAGE(PG8_SA(1, 0), cA + PG8_KOFFA(1), voffA); PG8_STAGE(PG8_SB(1, 1), cB + hstepB + kstep, voffB);
;     PG8_WAIT_V(6); PG8_BAR;
;     for (;;) {
;         const bool has_next = S.next(ui + 1, nxt);
;         const unsigned nA = has_next ? (unsigned)nxt.pm * tstepA : cA, nB = has_next ? (unsigned)nxt.pn * tstepB : cB;
.LBB0_468:
	ds_read_b128 v[148:151], v145
	ds_read_b128 v[152:155], v145 offset:1024
	ds_read_b128 v[156:159], v145 offset:2048
	ds_read_b128 v[160:163], v145 offset:3072
	ds_read_b128 v[164:167], v146
	ds_read_b128 v[168:171], v146 offset:1024
	ds_read_b128 v[172:175], v146 offset:2048
	ds_read_b128 v[176:179], v146 offset:3072
	s_cmp_eq_u32 s44, 12
	s_cselect_b32 s47, s0, s43
	s_cselect_b32 s46, s1, s42
	s_or_b32 s45, s47, 0x80
	v_mov_b32_e32 v135, v134
	ds_read_b128 v[180:183], v147
	ds_read_b128 v[192:195], v147 offset:1024
	ds_read_b128 v[196:199], v147 offset:2048
	ds_read_b128 v[200:203], v147 offset:3072
	ds_read_b128 v[204:207], v147 offset:4096
	ds_read_b128 v[208:211], v147 offset:5120
	ds_read_b128 v[212:215], v147 offset:6144
	ds_read_b128 v[216:219], v147 offset:7168
	s_add_i32 m0, s22, 0xc000
	s_nop 0
	global_load_lds_dwordx4 v135, s[10:11]
	v_mov_b32_e32 v135, v132
	s_add_i32 m0, s22, 0xe000
	s_nop 0
	global_load_lds_dwordx4 v135, s[10:11]
	s_waitcnt vmcnt(8)
	s_waitcnt lgkmcnt(0)
	s_barrier
	s_setprio 1
	s_waitcnt lgkmcnt(0)
	v_mfma_f32_16x16x32_bf16 v[124:127], v[148:151], v[180:183], v[124:127]
	v_mfma_f32_16x16x32_bf16 v[120:123], v[156:159], v[180:183], v[120:123]
	v_mfma_f32_16x16x32_bf16 v[108:111], v[148:151], v[196:199], v[108:111]
	v_mfma_f32_16x16x32_bf16 v[104:107], v[156:159], v[196:199], v[104:107]
	v_mfma_f32_16x16x32_bf16 v[92:95], v[148:151], v[204:207], v[92:95]
	v_mfma_f32_16x16x32_bf16 v[88:91], v[156:159], v[204:207], v[88:91]
	v_mfma_f32_16x16x32_bf16 v[76:79], v[148:151], v[212:215], v[76:79]
	v_mfma_f32_16x16x32_bf16 v[72:75], v[156:159], v[212:215], v[72:75]
	v_mfma_f32_16x16x32_bf16 v[124:127], v[152:155], v[192:195], v[124:127]
	v_mfma_f32_16x16x32_bf16 v[120:123], v[160:163], v[192:195], v[120:123]
	v_mfma_f32_16x16x32_bf16 v[108:111], v[152:155], v[200:203], v[108:111]
	v_mfma_f32_16x16x32_bf16 v[104:107], v[160:163], v[200:203], v[104:107]
	v_mfma_f32_16x16x32_bf16 v[92:95], v[152:155], v[208:211], v[92:95]
	v_mfma_f32_16x16x32_bf16 v[88:91], v[160:163], v[208:211], v[88:91]
	v_mfma_f32_16x16x32_bf16 v[76:79], v[152:155], v[216:219], v[76:79]
	v_mfma_f32_16x16x32_bf16 v[72:75], v[160:163], v[216:219], v[72:75]
	s_setprio 0
	s_setprio 1
	v_mfma_f32_16x16x32_bf16 v[116:119], v[164:167], v[180:183], v[116:119]
	v_mfma_f32_16x16x32_bf16 v[112:115], v[172:175], v[180:183], v[112:115]
	v_mfma_f32_16x16x32_bf16 v[100:103], v[164:167], v[196:199], v[100:103]
	v_mfma_f32_16x16x32_bf16 v[96:99], v[172:175], v[196:199], v[96:99]
	v_mfma_f32_16x16x32_bf16 v[84:87], v[164:167], v[204:207], v[84:87]
	v_mfma_f32_16x16x32_bf16 v[80:83], v[172:175], v[204:207], v[80:83]
	v_mfma_f32_16x16x32_bf16 v[68:71], v[164:167], v[212:215], v[68:71]
	v_mfma_f32_16x16x32_bf16 v[64:67], v[172:175], v[212:215], v[64:67]
	v_mfma_f32_16x16x32_bf16 v[116:119], v[168:171], v[192:195], v[116:119]
	v_mfma_f32_16x16x32_bf16 v[112:115], v[176:179], v[192:195], v[112:115]
	v_mfma_f32_16x16x32_bf16 v[100:103], v[168:171], v[200:203], v[100:103]
	v_mfma_f32_16x16x32_bf16 v[96:99], v[176:179], v[200:203], v[96:99]
	v_mfma_f32_16x16x32_bf16 v[84:87], v[168:171], v[208:211], v[84:87]
	v_mfma_f32_16x16x32_bf16 v[80:83], v[176:179], v[208:211], v[80:83]
	v_mfma_f32_16x16x32_bf16 v[68:71], v[168:171], v[216:219], v[68:71]
	v_mfma_f32_16x16x32_bf16 v[64:67], v[176:179], v[216:219], v[64:67]
	s_setprio 0
	s_barrier
	v_add_u32_e32 v135, s46, v137
	s_add_i32 s48, s35, s19
	ds_read_b128 v[180:183], v147 offset:16384
	ds_read_b128 v[192:195], v147 offset:17408
	ds_read_b128 v[196:199], v147 offset:18432
	ds_read_b128 v[200:203], v147 offset:19456
	ds_read_b128 v[204:207], v147 offset:20480
	ds_read_b128 v[208:211], v147 offset:21504
	ds_read_b128 v[212:215], v147 offset:22528
	ds_read_b128 v[216:219], v147 offset:23552
	s_mov_b32 m0, s48
	s_add_i32 s49, s36, s19
	global_load_lds_dwordx4 v135, s[12:13]
	v_add_u32_e32 v135, s46, v139
	s_add_i32 m0, s48, 0x2000
	s_add_i32 s48, s46, 0x40000
	global_load_lds_dwordx4 v135, s[12:13]
	v_add_u32_e32 v135, s48, v137
	s_mov_b32 m0, s49
	s_nop 0
	global_load_lds_dwordx4 v135, s[12:13]
	v_add_u32_e32 v135, s48, v139
	s_add_i32 m0, s49, 0x2000
	s_nop 0
	global_load_lds_dwordx4 v135, s[12:13]
	v_add_u32_e32 v135, s47, v136
	s_mov_b32 m0, s22
	s_nop 0
	global_load_lds_dwordx4 v135, s[10:11]
	v_add_u32_e32 v135, s47, v138
	s_mov_b32 m0, s23
	s_nop 0
	global_load_lds_dwordx4 v135, s[10:11]
	s_waitcnt vmcnt(8)
	s_waitcnt lgkmcnt(0)
	s_barrier
	s_setprio 1
	s_waitcnt lgkmcnt(0)
	v_mfma_f32_16x16x32_bf16 v[60:63], v[148:151], v[180:183], v[60:63]
	v_mfma_f32_16x16x32_bf16 v[56:59], v[156:159], v[180:183], v[56:59]
	v_mfma_f32_16x16x32_bf16 v[44:47], v[148:151], v[196:199], v[44:47]
	v_mfma_f32_16x16x32_bf16 v[40:43], v[156:159], v[196:199], v[40:43]
	v_mfma_f32_16x16x32_bf16 v[28:31], v[148:151], v[204:207], v[28:31]
	v_mfma_f32_16x16x32_bf16 v[24:27], v[156:159], v[204:207], v[24:27]
	v_mfma_f32_16x16x32_bf16 v[12:15], v[148:151], v[212:215], v[12:15]
	v_mfma_f32_16x16x32_bf16 v[8:11], v[156:159], v[212:215], v[8:11]
	v_mfma_f32_16x16x32_bf16 v[60:63], v[152:155], v[192:195], v[60:63]
	v_mfma_f32_16x16x32_bf16 v[56:59], v[160:163], v[192:195], v[56:59]
	v_mfma_f32_16x16x32_bf16 v[44:47], v[152:155], v[200:203], v[44:47]
	v_mfma_f32_16x16x32_bf16 v[40:43], v[160:163], v[200:203], v[40:43]
	v_mfma_f32_16x16x32_bf16 v[28:31], v[152:155], v[208:211], v[28:31]
	v_mfma_f32_16x16x32_bf16 v[24:27], v[160:163], v[208:211], v[24:27]
	v_mfma_f32_16x16x32_bf16 v[12:15], v[152:155], v[216:219], v[12:15]
	v_mfma_f32_16x16x32_bf16 v[8:11], v[160:163], v[216:219], v[8:11]
	s_setprio 0
	s_setprio 1
	v_mfma_f32_16x16x32_bf16 v[52:55], v[164:167], v[180:183], v[52:55]
	v_mfma_f32_16x16x32_bf16 v[48:51], v[172:175], v[180:183], v[48:51]
	v_mfma_f32_16x16x32_bf16 v[36:39], v[164:167], v[196:199], v[36:39]
	v_mfma_f32_16x16x32_bf16 v[32:35], v[172:175], v[196:199], v[32:35]
	v_mfma_f32_16x16x32_bf16 v[20:23], v[164:167], v[204:207], v[20:23]
	v_mfma_f32_16x16x32_bf16 v[16:19], v[172:175], v[204:207], v[16:19]
	v_mfma_f32_16x16x32_bf16 v[4:7], v[164:167], v[212:215], v[4:7]
	v_mfma_f32_16x16x32_bf16 v[0:3], v[172:175], v[212:215], v[0:3]
	v_mfma_f32_16x16x32_bf16 v[52:55], v[168:171], v[192:195], v[52:55]
	v_mfma_f32_16x16x32_bf16 v[48:51], v[176:179], v[192:195], v[48:51]
	v_mfma_f32_16x16x32_bf16 v[36:39], v[168:171], v[200:203], v[36:39]
	v_mfma_f32_16x16x32_bf16 v[32:35], v[176:179], v[200:203], v[32:35]
	v_mfma_f32_16x16x32_bf16 v[20:23], v[168:171], v[208:211], v[20:23]
	v_mfma_f32_16x16x32_bf16 v[16:19], v[176:179], v[208:211], v[16:19]
	v_mfma_f32_16x16x32_bf16 v[4:7], v[168:171], v[216:219], v[4:7]
	v_mfma_f32_16x16x32_bf16 v[0:3], v[176:179], v[216:219], v[0:3]
	s_setprio 0
	s_barrier
;     ...
;         if constexpr (Epi::MIDHOOK) {
;             for (int t = 0; t < 4; t += 2) PG8_ITER(t);
;             E.mid(acc, cur, wr, wc, fr, fq);
;             for (int t = 4; t < nt; t += 2) PG8_ITER(t);
;         } else {
;             for (int t = 0; t < nt; t += 2) PG8_ITER(t);
	s_add_i32 s48, 0, 0x18000
	v_add_u32_e32 v135, s48, v141
	s_add_i32 s49, 0, 0x1c000
	ds_read_b128 v[148:151], v135
	ds_read_b128 v[152:155], v135 offset:1024
	ds_read_b128 v[156:159], v135 offset:2048
	ds_read_b128 v[160:163], v135 offset:3072
	v_add_u32_e32 v135, s49, v141
	ds_read_b128 v[164:167], v135
	ds_read_b128 v[168:171], v135 offset:1024
	ds_read_b128 v[172:175], v135 offset:2048
	ds_read_b128 v[176:179], v135 offset:3072
	s_add_i32 s47, s47, 0x40000
	v_add_u32_e32 v135, s47, v136
	s_mov_b32 m0, s24
	ds_read_b128 v[180:183], v147 offset:32768
	ds_read_b128 v[192:195], v147 offset:33792
	ds_read_b128 v[196:199], v147 offset:34816
	ds_read_b128 v[200:203], v147 offset:35840
	ds_read_b128 v[204:207], v147 offset:36864
	ds_read_b128 v[208:211], v147 offset:37888
	ds_read_b128 v[212:215], v147 offset:38912
	ds_read_b128 v[216:219], v147 offset:39936
	s_nop 0
	global_load_lds_dwordx4 v135, s[10:11]
	v_add_u32_e32 v135, s47, v138
	s_mov_b32 m0, s25
	s_nop 0
	global_load_lds_dwordx4 v135, s[10:11]
	s_waitcnt vmcnt(8)
	s_waitcnt lgkmcnt(0)
	s_barrier
	s_setprio 1
	s_waitcnt lgkmcnt(0)
	v_mfma_f32_16x16x32_bf16 v[124:127], v[148:151], v[180:183], v[124:127]
	v_mfma_f32_16x16x32_bf16 v[120:123], v[156:159], v[180:183], v[120:123]
	v_mfma_f32_16x16x32_bf16 v[108:111], v[148:151], v[196:199], v[108:111]
	v_mfma_f32_16x16x32_bf16 v[104:107], v[156:159], v[196:199], v[104:107]
	v_mfma_f32_16x16x32_bf16 v[92:95], v[148:151], v[204:207], v[92:95]
	v_mfma_f32_16x16x32_bf16 v[88:91], v[156:159], v[204:207], v[88:91]
	v_mfma_f32_16x16x32_bf16 v[76:79], v[148:151], v[212:215], v[76:79]
	v_mfma_f32_16x16x32_bf16 v[72:75], v[156:159], v[212:215], v[72:75]
	v_mfma_f32_16x16x32_bf16 v[124:127], v[152:155], v[192:195], v[124:127]
	v_mfma_f32_16x16x32_bf16 v[120:123], v[160:163], v[192:195], v[120:123]
	v_mfma_f32_16x16x32_bf16 v[108:111], v[152:155], v[200:203], v[108:111]
	v_mfma_f32_16x16x32_bf16 v[104:107], v[160:163], v[200:203], v[104:107]
	v_mfma_f32_16x16x32_bf16 v[92:95], v[152:155], v[208:211], v[92:95]
	v_mfma_f32_16x16x32_bf16 v[88:91], v[160:163], v[208:211], v[88:91]
	v_mfma_f32_16x16x32_bf16 v[76:79], v[152:155], v[216:219], v[76:79]
	v_mfma_f32_16x16x32_bf16 v[72:75], v[160:163], v[216:219], v[72:75]
	s_setprio 0
	s_setprio 1
	v_mfma_f32_16x16x32_bf16 v[116:119], v[164:167], v[180:183], v[116:119]
	v_mfma_f32_16x16x32_bf16 v[112:115], v[172:175], v[180:183], v[112:115]
	v_mfma_f32_16x16x32_bf16 v[100:103], v[164:167], v[196:199], v[100:103]
	v_mfma_f32_16x16x32_bf16 v[96:99], v[172:175], v[196:199], v[96:99]
	v_mfma_f32_16x16x32_bf16 v[84:87], v[164:167], v[204:207], v[84:87]
	v_mfma_f32_16x16x32_bf16 v[80:83], v[172:175], v[204:207], v[80:83]
	v_mfma_f32_16x16x32_bf16 v[68:71], v[164:167], v[212:215], v[68:71]
	v_mfma_f32_16x16x32_bf16 v[64:67], v[172:175], v[212:215], v[64:67]
	v_mfma_f32_16x16x32_bf16 v[116:119], v[168:171], v[192:195], v[116:119]
	v_mfma_f32_16x16x32_bf16 v[112:115], v[176:179], v[192:195], v[112:115]
	v_mfma_f32_16x16x32_bf16 v[100:103], v[168:171], v[200:203], v[100:103]
	v_mfma_f32_16x16x32_bf16 v[96:99], v[176:179], v[200:203], v[96:99]
	v_mfma_f32_16x16x32_bf16 v[84:87], v[168:171], v[208:211], v[84:87]
	v_mfma_f32_16x16x32_bf16 v[80:83], v[176:179], v[208:211], v[80:83]
	v_mfma_f32_16x16x32_bf16 v[68:71], v[168:171], v[216:219], v[68:71]
	v_mfma_f32_16x16x32_bf16 v[64:67], v[176:179], v[216:219], v[64:67]
	s_setprio 0
	s_barrier
	s_or_b32 s47, s46, 0x80
	v_add_u32_e32 v135, s47, v137
	s_add_i32 s48, s48, s19
	ds_read_b128 v[180:183], v147 offset:49152
	ds_read_b128 v[192:195], v147 offset:50176
	ds_read_b128 v[196:199], v147 offset:51200
	ds_read_b128 v[200:203], v147 offset:52224
	ds_read_b128 v[204:207], v147 offset:53248
	ds_read_b128 v[208:211], v147 offset:54272
	ds_read_b128 v[212:215], v147 offset:55296
	ds_read_b128 v[216:219], v147 offset:56320
	s_mov_b32 m0, s48
	s_add_i32 s46, s46, 0x40080
	global_load_lds_dwordx4 v135, s[12:13]
	v_add_u32_e32 v135, s47, v139
	s_add_i32 m0, s48, 0x2000
	s_add_i32 s47, s49, s19
	global_load_lds_dwordx4 v135, s[12:13]
	v_add_u32_e32 v135, s46, v137
	s_mov_b32 m0, s47
	s_nop 0
	global_load_lds_dwordx4 v135, s[12:13]
	v_add_u32_e32 v135, s46, v139
	s_add_i32 m0, s47, 0x2000
	s_nop 0
	global_load_lds_dwordx4 v135, s[12:13]
	v_add_u32_e32 v135, s45, v136
	s_mov_b32 m0, s30
	s_nop 0
	global_load_lds_dwordx4 v135, s[10:11]
	v_add_u32_e32 v135, s45, v138
	s_mov_b32 m0, s31
	s_nop 0
	global_load_lds_dwordx4 v135, s[10:11]
	s_waitcnt vmcnt(8)
	s_waitcnt lgkmcnt(0)
	s_barrier
	s_setprio 1
	s_waitcnt lgkmcnt(0)
	v_mfma_f32_16x16x32_bf16 v[60:63], v[148:151], v[180:183], v[60:63]
	v_mfma_f32_16x16x32_bf16 v[56:59], v[156:159], v[180:183], v[56:59]
	v_mfma_f32_16x16x32_bf16 v[44:47], v[148:151], v[196:199], v[44:47]
	v_mfma_f32_16x16x32_bf16 v[40:43], v[156:159], v[196:199], v[40:43]
	v_mfma_f32_16x16x32_bf16 v[28:31], v[148:151], v[204:207], v[28:31]
	v_mfma_f32_16x16x32_bf16 v[24:27], v[156:159], v[204:207], v[24:27]
	v_mfma_f32_16x16x32_bf16 v[12:15], v[148:151], v[212:215], v[12:15]
	v_mfma_f32_16x16x32_bf16 v[8:11], v[156:159], v[212:215], v[8:11]
	v_mfma_f32_16x16x32_bf16 v[60:63], v[152:155], v[192:195], v[60:63]
	v_mfma_f32_16x16x32_bf16 v[56:59], v[160:163], v[192:195], v[56:59]
	v_mfma_f32_16x16x32_bf16 v[44:47], v[152:155], v[200:203], v[44:47]
	v_mfma_f32_16x16x32_bf16 v[40:43], v[160:163], v[200:203], v[40:43]
	v_mfma_f32_16x16x32_bf16 v[28:31], v[152:155], v[208:211], v[28:31]
	v_mfma_f32_16x16x32_bf16 v[24:27], v[160:163], v[208:211], v[24:27]
	v_mfma_f32_16x16x32_bf16 v[12:15], v[152:155], v[216:219], v[12:15]
	v_mfma_f32_16x16x32_bf16 v[8:11], v[160:163], v[216:219], v[8:11]
	s_setprio 0
	s_setprio 1
	v_mfma_f32_16x16x32_bf16 v[52:55], v[164:167], v[180:183], v[52:55]
	v_mfma_f32_16x16x32_bf16 v[48:51], v[172:175], v[180:183], v[48:51]
	v_mfma_f32_16x16x32_bf16 v[36:39], v[164:167], v[196:199], v[36:39]
	v_mfma_f32_16x16x32_bf16 v[32:35], v[172:175], v[196:199], v[32:35]
	v_mfma_f32_16x16x32_bf16 v[20:23], v[164:167], v[204:207], v[20:23]
	v_mfma_f32_16x16x32_bf16 v[16:19], v[172:175], v[204:207], v[16:19]
	v_mfma_f32_16x16x32_bf16 v[4:7], v[164:167], v[212:215], v[4:7]
	v_mfma_f32_16x16x32_bf16 v[0:3], v[172:175], v[212:215], v[0:3]
	v_mfma_f32_16x16x32_bf16 v[52:55], v[168:171], v[192:195], v[52:55]
	v_mfma_f32_16x16x32_bf16 v[48:51], v[176:179], v[192:195], v[48:51]
	v_mfma_f32_16x16x32_bf16 v[36:39], v[168:171], v[200:203], v[36:39]
	v_mfma_f32_16x16x32_bf16 v[32:35], v[176:179], v[200:203], v[32:35]
	v_mfma_f32_16x16x32_bf16 v[20:23], v[168:171], v[208:211], v[20:23]
	v_mfma_f32_16x16x32_bf16 v[16:19], v[176:179], v[208:211], v[16:19]
	v_mfma_f32_16x16x32_bf16 v[4:7], v[168:171], v[216:219], v[4:7]
	v_mfma_f32_16x16x32_bf16 v[0:3], v[176:179], v[216:219], v[0:3]
	s_setprio 0
	s_add_i32 s44, s44, 2
	s_addk_i32 s42, 0x100
	s_addk_i32 s43, 0x100
	v_add_u32_e32 v132, 0x100, v132
	s_cmp_gt_u32 s44, 13
	v_add_u32_e32 v134, 0x100, v134
	s_barrier
	s_cbranch_scc0 .LBB0_468
	s_and_b64 vcc, exec, s[16:17]
	s_cbranch_vccz .LBB0_471
	s_barrier

; #define PG8_STAGE(bufoff, goff, voff) do { _Pragma("unroll") for (int _i = 0; _i < 2; ++_i) { unsigned _vo = (voff)[_i] + (goff); asm volatile("" : "+v"(_vo)); \
;         __builtin_amdgcn_global_load_lds((const unsigned*)(base_##voff + _vo), (LAS unsigned*)(lds + (bufoff) + ldsw + _i * 8192), 16, 0, 0); } } while (0)
; #define PG8_WAIT_V(n) asm volatile("s_waitcnt vmcnt(" #n ")" ::: "memory")
; #define PG8_BAR __builtin_amdgcn_s_barrier()
;     ...
;     Unit cur, nxt; int ui = 0;
;     if (!S.next(0, cur)) return;
;     f32x4 acc[2][2][4][2];
; #pragma unroll
;     for (int a = 0; a < 2; ++a)
; #pragma unroll
;         for (int b = 0; b < 2; ++b)
; #pragma unroll
;             for (int m = 0; m < 4; ++m)
; #pragma unroll
;                 for (int n = 0; n < 2; ++n) acc[a][b][m][n] = (f32x4){0.f, 0.f, 0.f, 0.f};
;     bf16x8 At[4][2], B0[2][2], B1[2][2];
;     unsigned cA = (unsigned)cur.pm * tstepA, cB = (unsigned)cur.pn * tstepB;
;     PG8_STAGE(PG8_SB(0, 0), cB, voffB); PG8_STAGE(PG8_SB(0, 1), cB + hstepB, voffB); PG8_STAGE(PG8_SA(0, 0), cA + PG8_KOFFA(0), voffA); PG8_STAGE(PG8_SA(0, 1), cA + hstepA + PG8_KOFFA(0), voffA);
;     if (wr == 1) PG8_BAR;
;     PG8_WAIT_V(2); PG8_BAR;
;     PG8_STAGE(PG8_SB(1, 0), cB + kstep, voffB); PG8_STAGE(PG8_SA(1, 0), cA + PG8_KOFFA(1), voffA); PG8_STAGE(PG8_SB(1, 1), cB + hstepB + kstep, voffB);
;     PG8_WAIT_V(6); PG8_BAR;
;     for (;;) {
;         const bool has_next = S.next(ui + 1, nxt);
;         const unsigned nA = has_next ? (unsigned)nxt.pm * tstepA : cA, nB = has_next ? (unsigned)nxt.pn * tstepB : cB;
.LBB0_523:
	ds_read_b128 v[148:151], v145
	ds_read_b128 v[152:155], v145 offset:1024
	ds_read_b128 v[156:159], v145 offset:2048
	ds_read_b128 v[160:163], v145 offset:3072
	ds_read_b128 v[164:167], v146
	ds_read_b128 v[168:171], v146 offset:1024
	ds_read_b128 v[172:175], v146 offset:2048
	ds_read_b128 v[176:179], v146 offset:3072
	s_cmp_eq_u32 s40, 12
	s_cselect_b32 s43, s0, s39
	s_cselect_b32 s42, s1, s38
	s_or_b32 s41, s43, 0x80
	v_mov_b32_e32 v135, v134
	ds_read_b128 v[180:183], v147
	ds_read_b128 v[192:195], v147 offset:1024
	ds_read_b128 v[196:199], v147 offset:2048
	ds_read_b128 v[200:203], v147 offset:3072
	ds_read_b128 v[204:207], v147 offset:4096
	ds_read_b128 v[208:211], v147 offset:5120
	ds_read_b128 v[212:215], v147 offset:6144
	ds_read_b128 v[216:219], v147 offset:7168
	s_add_i32 m0, s18, 0xc000
	s_nop 0
	global_load_lds_dwordx4 v135, s[8:9]
	v_mov_b32_e32 v135, v132
	s_add_i32 m0, s18, 0xe000
	s_nop 0
	global_load_lds_dwordx4 v135, s[8:9]
	s_waitcnt vmcnt(8)
	s_waitcnt lgkmcnt(0)
	s_barrier
	s_setprio 1
	s_waitcnt lgkmcnt(0)
	v_mfma_f32_16x16x32_bf16 v[124:127], v[148:151], v[180:183], v[124:127]
	v_mfma_f32_16x16x32_bf16 v[120:123], v[156:159], v[180:183], v[120:123]
	v_mfma_f32_16x16x32_bf16 v[108:111], v[148:151], v[196:199], v[108:111]
	v_mfma_f32_16x16x32_bf16 v[104:107], v[156:159], v[196:199], v[104:107]
	v_mfma_f32_16x16x32_bf16 v[92:95], v[148:151], v[204:207], v[92:95]
	v_mfma_f32_16x16x32_bf16 v[88:91], v[156:159], v[204:207], v[88:91]
	v_mfma_f32_16x16x32_bf16 v[76:79], v[148:151], v[212:215], v[76:79]
	v_mfma_f32_16x16x32_bf16 v[72:75], v[156:159], v[212:215], v[72:75]
	v_mfma_f32_16x16x32_bf16 v[124:127], v[152:155], v[192:195], v[124:127]
	v_mfma_f32_16x16x32_bf16 v[120:123], v[160:163], v[192:195], v[120:123]
	v_mfma_f32_16x16x32_bf16 v[108:111], v[152:155], v[200:203], v[108:111]
	v_mfma_f32_16x16x32_bf16 v[104:107], v[160:163], v[200:203], v[104:107]
	v_mfma_f32_16x16x32_bf16 v[92:95], v[152:155], v[208:211], v[92:95]
	v_mfma_f32_16x16x32_bf16 v[88:91], v[160:163], v[208:211], v[88:91]
	v_mfma_f32_16x16x32_bf16 v[76:79], v[152:155], v[216:219], v[76:79]
	v_mfma_f32_16x16x32_bf16 v[72:75], v[160:163], v[216:219], v[72:75]
	s_setprio 0
	s_setprio 1
	v_mfma_f32_16x16x32_bf16 v[116:119], v[164:167], v[180:183], v[116:119]
	v_mfma_f32_16x16x32_bf16 v[112:115], v[172:175], v[180:183], v[112:115]
	v_mfma_f32_16x16x32_bf16 v[100:103], v[164:167], v[196:199], v[100:103]
	v_mfma_f32_16x16x32_bf16 v[96:99], v[172:175], v[196:199], v[96:99]
	v_mfma_f32_16x16x32_bf16 v[84:87], v[164:167], v[204:207], v[84:87]
	v_mfma_f32_16x16x32_bf16 v[80:83], v[172:175], v[204:207], v[80:83]
	v_mfma_f32_16x16x32_bf16 v[68:71], v[164:167], v[212:215], v[68:71]
	v_mfma_f32_16x16x32_bf16 v[64:67], v[172:175], v[212:215], v[64:67]
	v_mfma_f32_16x16x32_bf16 v[116:119], v[168:171], v[192:195], v[116:119]
	v_mfma_f32_16x16x32_bf16 v[112:115], v[176:179], v[192:195], v[112:115]
	v_mfma_f32_16x16x32_bf16 v[100:103], v[168:171], v[200:203], v[100:103]
	v_mfma_f32_16x16x32_bf16 v[96:99], v[176:179], v[200:203], v[96:99]
	v_mfma_f32_16x16x32_bf16 v[84:87], v[168:171], v[208:211], v[84:87]
	v_mfma_f32_16x16x32_bf16 v[80:83], v[176:179], v[208:211], v[80:83]
	v_mfma_f32_16x16x32_bf16 v[68:71], v[168:171], v[216:219], v[68:71]
	v_mfma_f32_16x16x32_bf16 v[64:67], v[176:179], v[216:219], v[64:67]
	s_setprio 0
	s_barrier
	v_add_u32_e32 v135, s42, v137
	s_add_i32 s44, s30, s17
	ds_read_b128 v[180:183], v147 offset:16384
	ds_read_b128 v[192:195], v147 offset:17408
	ds_read_b128 v[196:199], v147 offset:18432
	ds_read_b128 v[200:203], v147 offset:19456
	ds_read_b128 v[204:207], v147 offset:20480
	ds_read_b128 v[208:211], v147 offset:21504
	ds_read_b128 v[212:215], v147 offset:22528
	ds_read_b128 v[216:219], v147 offset:23552
	s_mov_b32 m0, s44
	s_add_i32 s45, s31, s17
	global_load_lds_dwordx4 v135, s[10:11]
	v_add_u32_e32 v135, s42, v139
	s_add_i32 m0, s44, 0x2000
	s_add_i32 s44, s42, 0x40000
	global_load_lds_dwordx4 v135, s[10:11]
	v_add_u32_e32 v135, s44, v137
	s_mov_b32 m0, s45
	s_nop 0
	global_load_lds_dwordx4 v135, s[10:11]
	v_add_u32_e32 v135, s44, v139
	s_add_i32 m0, s45, 0x2000
	s_nop 0
	global_load_lds_dwordx4 v135, s[10:11]
	v_add_u32_e32 v135, s43, v136
	s_mov_b32 m0, s18
	s_nop 0
	global_load_lds_dwordx4 v135, s[8:9]
	v_add_u32_e32 v135, s43, v138
	s_mov_b32 m0, s19
	s_nop 0
	global_load_lds_dwordx4 v135, s[8:9]
	s_waitcnt vmcnt(8)
	s_waitcnt lgkmcnt(0)
	s_barrier
	s_setprio 1
	s_waitcnt lgkmcnt(0)
	v_mfma_f32_16x16x32_bf16 v[60:63], v[148:151], v[180:183], v[60:63]
	v_mfma_f32_16x16x32_bf16 v[56:59], v[156:159], v[180:183], v[56:59]
	v_mfma_f32_16x16x32_bf16 v[44:47], v[148:151], v[196:199], v[44:47]
	v_mfma_f32_16x16x32_bf16 v[40:43], v[156:159], v[196:199], v[40:43]
	v_mfma_f32_16x16x32_bf16 v[28:31], v[148:151], v[204:207], v[28:31]
	v_mfma_f32_16x16x32_bf16 v[24:27], v[156:159], v[204:207], v[24:27]
	v_mfma_f32_16x16x32_bf16 v[12:15], v[148:151], v[212:215], v[12:15]
	v_mfma_f32_16x16x32_bf16 v[8:11], v[156:159], v[212:215], v[8:11]
	v_mfma_f32_16x16x32_bf16 v[60:63], v[152:155], v[192:195], v[60:63]
	v_mfma_f32_16x16x32_bf16 v[56:59], v[160:163], v[192:195], v[56:59]
	v_mfma_f32_16x16x32_bf16 v[44:47], v[152:155], v[200:203], v[44:47]
	v_mfma_f32_16x16x32_bf16 v[40:43], v[160:163], v[200:203], v[40:43]
	v_mfma_f32_16x16x32_bf16 v[28:31], v[152:155], v[208:211], v[28:31]
	v_mfma_f32_16x16x32_bf16 v[24:27], v[160:163], v[208:211], v[24:27]
	v_mfma_f32_16x16x32_bf16 v[12:15], v[152:155], v[216:219], v[12:15]
	v_mfma_f32_16x16x32_bf16 v[8:11], v[160:163], v[216:219], v[8:11]
	s_setprio 0
	s_setprio 1
	v_mfma_f32_16x16x32_bf16 v[52:55], v[164:167], v[180:183], v[52:55]
	v_mfma_f32_16x16x32_bf16 v[48:51], v[172:175], v[180:183], v[48:51]
	v_mfma_f32_16x16x32_bf16 v[36:39], v[164:167], v[196:199], v[36:39]
	v_mfma_f32_16x16x32_bf16 v[32:35], v[172:175], v[196:199], v[32:35]
	v_mfma_f32_16x16x32_bf16 v[20:23], v[164:167], v[204:207], v[20:23]
	v_mfma_f32_16x16x32_bf16 v[16:19], v[172:175], v[204:207], v[16:19]
	v_mfma_f32_16x16x32_bf16 v[4:7], v[164:167], v[212:215], v[4:7]
	v_mfma_f32_16x16x32_bf16 v[0:3], v[172:175], v[212:215], v[0:3]
	v_mfma_f32_16x16x32_bf16 v[52:55], v[168:171], v[192:195], v[52:55]
	v_mfma_f32_16x16x32_bf16 v[48:51], v[176:179], v[192:195], v[48:51]
	v_mfma_f32_16x16x32_bf16 v[36:39], v[168:171], v[200:203], v[36:39]
	v_mfma_f32_16x16x32_bf16 v[32:35], v[176:179], v[200:203], v[32:35]
	v_mfma_f32_16x16x32_bf16 v[20:23], v[168:171], v[208:211], v[20:23]
	v_mfma_f32_16x16x32_bf16 v[16:19], v[176:179], v[208:211], v[16:19]
	v_mfma_f32_16x16x32_bf16 v[4:7], v[168:171], v[216:219], v[4:7]
	v_mfma_f32_16x16x32_bf16 v[0:3], v[176:179], v[216:219], v[0:3]
	s_setprio 0
	s_barrier
;     ...
;         if constexpr (Epi::MIDHOOK) {
;             for (int t = 0; t < 4; t += 2) PG8_ITER(t);
;             E.mid(acc, cur, wr, wc, fr, fq);
;             for (int t = 4; t < nt; t += 2) PG8_ITER(t);
;         } else {
;             for (int t = 0; t < nt; t += 2) PG8_ITER(t);
	s_add_i32 s44, 0, 0x18000
	v_add_u32_e32 v135, s44, v141
	s_add_i32 s45, 0, 0x1c000
	ds_read_b128 v[148:151], v135
	ds_read_b128 v[152:155], v135 offset:1024
	ds_read_b128 v[156:159], v135 offset:2048
	ds_read_b128 v[160:163], v135 offset:3072
	v_add_u32_e32 v135, s45, v141
	ds_read_b128 v[164:167], v135
	ds_read_b128 v[168:171], v135 offset:1024
	ds_read_b128 v[172:175], v135 offset:2048
	ds_read_b128 v[176:179], v135 offset:3072
	s_add_i32 s43, s43, 0x40000
	v_add_u32_e32 v135, s43, v136
	s_mov_b32 m0, s20
	ds_read_b128 v[180:183], v147 offset:32768
	ds_read_b128 v[192:195], v147 offset:33792
	ds_read_b128 v[196:199], v147 offset:34816
	ds_read_b128 v[200:203], v147 offset:35840
	ds_read_b128 v[204:207], v147 offset:36864
	ds_read_b128 v[208:211], v147 offset:37888
	ds_read_b128 v[212:215], v147 offset:38912
	ds_read_b128 v[216:219], v147 offset:39936
	s_nop 0
	global_load_lds_dwordx4 v135, s[8:9]
	v_add_u32_e32 v135, s43, v138
	s_mov_b32 m0, s21
	s_nop 0
	global_load_lds_dwordx4 v135, s[8:9]
	s_waitcnt vmcnt(8)
	s_waitcnt lgkmcnt(0)
	s_barrier
	s_setprio 1
	s_waitcnt lgkmcnt(0)
	v_mfma_f32_16x16x32_bf16 v[124:127], v[148:151], v[180:183], v[124:127]
	v_mfma_f32_16x16x32_bf16 v[120:123], v[156:159], v[180:183], v[120:123]
	v_mfma_f32_16x16x32_bf16 v[108:111], v[148:151], v[196:199], v[108:111]
	v_mfma_f32_16x16x32_bf16 v[104:107], v[156:159], v[196:199], v[104:107]
	v_mfma_f32_16x16x32_bf16 v[92:95], v[148:151], v[204:207], v[92:95]
	v_mfma_f32_16x16x32_bf16 v[88:91], v[156:159], v[204:207], v[88:91]
	v_mfma_f32_16x16x32_bf16 v[76:79], v[148:151], v[212:215], v[76:79]
	v_mfma_f32_16x16x32_bf16 v[72:75], v[156:159], v[212:215], v[72:75]
	v_mfma_f32_16x16x32_bf16 v[124:127], v[152:155], v[192:195], v[124:127]
	v_mfma_f32_16x16x32_bf16 v[120:123], v[160:163], v[192:195], v[120:123]
	v_mfma_f32_16x16x32_bf16 v[108:111], v[152:155], v[200:203], v[108:111]
	v_mfma_f32_16x16x32_bf16 v[104:107], v[160:163], v[200:203], v[104:107]
	v_mfma_f32_16x16x32_bf16 v[92:95], v[152:155], v[208:211], v[92:95]
	v_mfma_f32_16x16x32_bf16 v[88:91], v[160:163], v[208:211], v[88:91]
	v_mfma_f32_16x16x32_bf16 v[76:79], v[152:155], v[216:219], v[76:79]
	v_mfma_f32_16x16x32_bf16 v[72:75], v[160:163], v[216:219], v[72:75]
	s_setprio 0
	s_setprio 1
	v_mfma_f32_16x16x32_bf16 v[116:119], v[164:167], v[180:183], v[116:119]
	v_mfma_f32_16x16x32_bf16 v[112:115], v[172:175], v[180:183], v[112:115]
	v_mfma_f32_16x16x32_bf16 v[100:103], v[164:167], v[196:199], v[100:103]
	v_mfma_f32_16x16x32_bf16 v[96:99], v[172:175], v[196:199], v[96:99]
	v_mfma_f32_16x16x32_bf16 v[84:87], v[164:167], v[204:207], v[84:87]
	v_mfma_f32_16x16x32_bf16 v[80:83], v[172:175], v[204:207], v[80:83]
	v_mfma_f32_16x16x32_bf16 v[68:71], v[164:167], v[212:215], v[68:71]
	v_mfma_f32_16x16x32_bf16 v[64:67], v[172:175], v[212:215], v[64:67]
	v_mfma_f32_16x16x32_bf16 v[116:119], v[168:171], v[192:195], v[116:119]
	v_mfma_f32_16x16x32_bf16 v[112:115], v[176:179], v[192:195], v[112:115]
	v_mfma_f32_16x16x32_bf16 v[100:103], v[168:171], v[200:203], v[100:103]
	v_mfma_f32_16x16x32_bf16 v[96:99], v[176:179], v[200:203], v[96:99]
	v_mfma_f32_16x16x32_bf16 v[84:87], v[168:171], v[208:211], v[84:87]
	v_mfma_f32_16x16x32_bf16 v[80:83], v[176:179], v[208:211], v[80:83]
	v_mfma_f32_16x16x32_bf16 v[68:71], v[168:171], v[216:219], v[68:71]
	v_mfma_f32_16x16x32_bf16 v[64:67], v[176:179], v[216:219], v[64:67]
	s_setprio 0
	s_barrier
	s_or_b32 s43, s42, 0x80
	v_add_u32_e32 v135, s43, v137
	s_add_i32 s44, s44, s17
	ds_read_b128 v[180:183], v147 offset:49152
	ds_read_b128 v[192:195], v147 offset:50176
	ds_read_b128 v[196:199], v147 offset:51200
	ds_read_b128 v[200:203], v147 offset:52224
	ds_read_b128 v[204:207], v147 offset:53248
	ds_read_b128 v[208:211], v147 offset:54272
	ds_read_b128 v[212:215], v147 offset:55296
	ds_read_b128 v[216:219], v147 offset:56320
	s_mov_b32 m0, s44
	s_add_i32 s42, s42, 0x40080
	global_load_lds_dwordx4 v135, s[10:11]
	v_add_u32_e32 v135, s43, v139
	s_add_i32 m0, s44, 0x2000
	s_add_i32 s43, s45, s17
	global_load_lds_dwordx4 v135, s[10:11]
	v_add_u32_e32 v135, s42, v137
	s_mov_b32 m0, s43
	s_nop 0
	global_load_lds_dwordx4 v135, s[10:11]
	v_add_u32_e32 v135, s42, v139
	s_add_i32 m0, s43, 0x2000
	s_nop 0
	global_load_lds_dwordx4 v135, s[10:11]
	v_add_u32_e32 v135, s41, v136
	s_mov_b32 m0, s26
	s_nop 0
	global_load_lds_dwordx4 v135, s[8:9]
	v_add_u32_e32 v135, s41, v138
	s_mov_b32 m0, s27
	s_nop 0
	global_load_lds_dwordx4 v135, s[8:9]
	s_waitcnt vmcnt(8)
	s_waitcnt lgkmcnt(0)
	s_barrier
	s_setprio 1
	s_waitcnt lgkmcnt(0)
	v_mfma_f32_16x16x32_bf16 v[60:63], v[148:151], v[180:183], v[60:63]
	v_mfma_f32_16x16x32_bf16 v[56:59], v[156:159], v[180:183], v[56:59]
	v_mfma_f32_16x16x32_bf16 v[44:47], v[148:151], v[196:199], v[44:47]
	v_mfma_f32_16x16x32_bf16 v[40:43], v[156:159], v[196:199], v[40:43]
	v_mfma_f32_16x16x32_bf16 v[28:31], v[148:151], v[204:207], v[28:31]
	v_mfma_f32_16x16x32_bf16 v[24:27], v[156:159], v[204:207], v[24:27]
	v_mfma_f32_16x16x32_bf16 v[12:15], v[148:151], v[212:215], v[12:15]
	v_mfma_f32_16x16x32_bf16 v[8:11], v[156:159], v[212:215], v[8:11]
	v_mfma_f32_16x16x32_bf16 v[60:63], v[152:155], v[192:195], v[60:63]
	v_mfma_f32_16x16x32_bf16 v[56:59], v[160:163], v[192:195], v[56:59]
	v_mfma_f32_16x16x32_bf16 v[44:47], v[152:155], v[200:203], v[44:47]
	v_mfma_f32_16x16x32_bf16 v[40:43], v[160:163], v[200:203], v[40:43]
	v_mfma_f32_16x16x32_bf16 v[28:31], v[152:155], v[208:211], v[28:31]
	v_mfma_f32_16x16x32_bf16 v[24:27], v[160:163], v[208:211], v[24:27]
	v_mfma_f32_16x16x32_bf16 v[12:15], v[152:155], v[216:219], v[12:15]
	v_mfma_f32_16x16x32_bf16 v[8:11], v[160:163], v[216:219], v[8:11]
	s_setprio 0
	s_setprio 1
	v_mfma_f32_16x16x32_bf16 v[52:55], v[164:167], v[180:183], v[52:55]
	v_mfma_f32_16x16x32_bf16 v[48:51], v[172:175], v[180:183], v[48:51]
	v_mfma_f32_16x16x32_bf16 v[36:39], v[164:167], v[196:199], v[36:39]
	v_mfma_f32_16x16x32_bf16 v[32:35], v[172:175], v[196:199], v[32:35]
	v_mfma_f32_16x16x32_bf16 v[20:23], v[164:167], v[204:207], v[20:23]
	v_mfma_f32_16x16x32_bf16 v[16:19], v[172:175], v[204:207], v[16:19]
	v_mfma_f32_16x16x32_bf16 v[4:7], v[164:167], v[212:215], v[4:7]
	v_mfma_f32_16x16x32_bf16 v[0:3], v[172:175], v[212:215], v[0:3]
	v_mfma_f32_16x16x32_bf16 v[52:55], v[168:171], v[192:195], v[52:55]
	v_mfma_f32_16x16x32_bf16 v[48:51], v[176:179], v[192:195], v[48:51]
	v_mfma_f32_16x16x32_bf16 v[36:39], v[168:171], v[200:203], v[36:39]
	v_mfma_f32_16x16x32_bf16 v[32:35], v[176:179], v[200:203], v[32:35]
	v_mfma_f32_16x16x32_bf16 v[20:23], v[168:171], v[208:211], v[20:23]
	v_mfma_f32_16x16x32_bf16 v[16:19], v[176:179], v[208:211], v[16:19]
	v_mfma_f32_16x16x32_bf16 v[4:7], v[168:171], v[216:219], v[4:7]
	v_mfma_f32_16x16x32_bf16 v[0:3], v[176:179], v[216:219], v[0:3]
	s_setprio 0
	s_add_i32 s40, s40, 2
	s_addk_i32 s38, 0x100
	s_addk_i32 s39, 0x100
	v_add_u32_e32 v132, 0x100, v132
	s_cmp_gt_u32 s40, 13
	v_add_u32_e32 v134, 0x100, v134
	s_barrier
	s_cbranch_scc0 .LBB0_523
	s_and_b64 vcc, exec, s[14:15]
	s_cbranch_vccz .LBB0_526
	s_barrier

; #define PG8_STAGE(bufoff, goff, voff) do { _Pragma("unroll") for (int _i = 0; _i < 2; ++_i) { unsigned _vo = (voff)[_i] + (goff); asm volatile("" : "+v"(_vo)); \
;         __builtin_amdgcn_global_load_lds((const unsigned*)(base_##voff + _vo), (LAS unsigned*)(lds + (bufoff) + ldsw + _i * 8192), 16, 0, 0); } } while (0)
; #define PG8_WAIT_V(n) asm volatile("s_waitcnt vmcnt(" #n ")" ::: "memory")
; #define PG8_BAR __builtin_amdgcn_s_barrier()
;     ...
;     Unit cur, nxt; int ui = 0;
;     if (!S.next(0, cur)) return;
;     f32x4 acc[2][2][4][2];
; #pragma unroll
;     for (int a = 0; a < 2; ++a)
; #pragma unroll
;         for (int b = 0; b < 2; ++b)
; #pragma unroll
;             for (int m = 0; m < 4; ++m)
; #pragma unroll
;                 for (int n = 0; n < 2; ++n) acc[a][b][m][n] = (f32x4){0.f, 0.f, 0.f, 0.f};
;     bf16x8 At[4][2], B0[2][2], B1[2][2];
;     unsigned cA = (unsigned)cur.pm * tstepA, cB = (unsigned)cur.pn * tstepB;
;     PG8_STAGE(PG8_SB(0, 0), cB, voffB); PG8_STAGE(PG8_SB(0, 1), cB + hstepB, voffB); PG8_STAGE(PG8_SA(0, 0), cA + PG8_KOFFA(0), voffA); PG8_STAGE(PG8_SA(0, 1), cA + hstepA + PG8_KOFFA(0), voffA);
;     if (wr == 1) PG8_BAR;
;     PG8_WAIT_V(2); PG8_BAR;
;     PG8_STAGE(PG8_SB(1, 0), cB + kstep, voffB); PG8_STAGE(PG8_SA(1, 0), cA + PG8_KOFFA(1), voffA); PG8_STAGE(PG8_SB(1, 1), cB + hstepB + kstep, voffB);
;     PG8_WAIT_V(6); PG8_BAR;
;     for (;;) {
;         const bool has_next = S.next(ui + 1, nxt);
;         const unsigned nA = has_next ? (unsigned)nxt.pm * tstepA : cA, nB = has_next ? (unsigned)nxt.pn * tstepB : cB;
.LBB0_599:
	ds_read_b128 v[36:39], v195
	ds_read_b128 v[132:135], v195 offset:1024
	ds_read_b128 v[138:141], v195 offset:2048
	ds_read_b128 v[142:145], v195 offset:3072
	ds_read_b128 v[146:149], v196
	ds_read_b128 v[154:157], v196 offset:1024
	ds_read_b128 v[158:161], v196 offset:2048
	ds_read_b128 v[198:201], v196 offset:3072
	s_add_i32 s52, s44, 0xffeb0080
	s_cmp_eq_u32 s51, 16
	s_cselect_b32 s54, s50, s52
	s_cselect_b32 s53, s49, s43
	s_or_b32 s52, s54, 0x80
	v_add_u32_e32 v137, s44, v194
	s_mov_b32 m0, s0
	ds_read_b128 v[202:205], v191
	ds_read_b128 v[206:209], v191 offset:1024
	ds_read_b128 v[210:213], v191 offset:2048
	ds_read_b128 v[214:217], v191 offset:3072
	ds_read_b128 v[218:221], v191 offset:4096
	ds_read_b128 v[222:225], v191 offset:5120
	ds_read_b128 v[226:229], v191 offset:6144
	ds_read_b128 v[230:233], v191 offset:7168
	s_nop 0
	global_load_lds_dwordx4 v137, s[12:13]
	v_add_u32_e32 v137, s44, v193
	s_mov_b32 m0, s1
	s_nop 0
	global_load_lds_dwordx4 v137, s[12:13]
	s_waitcnt vmcnt(8)
	s_waitcnt lgkmcnt(0)
	s_barrier
	s_setprio 1
	s_waitcnt lgkmcnt(0)
	v_mfma_f32_16x16x32_bf16 v[4:7], v[36:39], v[202:205], v[4:7]
	v_mfma_f32_16x16x32_bf16 v[0:3], v[138:141], v[202:205], v[0:3]
	v_mfma_f32_16x16x32_bf16 v[28:31], v[36:39], v[210:213], v[28:31]
	v_mfma_f32_16x16x32_bf16 v[24:27], v[138:141], v[210:213], v[24:27]
	v_mfma_f32_16x16x32_bf16 v[60:63], v[36:39], v[218:221], v[60:63]
	v_mfma_f32_16x16x32_bf16 v[56:59], v[138:141], v[218:221], v[56:59]
	v_mfma_f32_16x16x32_bf16 v[84:87], v[36:39], v[226:229], v[84:87]
	v_mfma_f32_16x16x32_bf16 v[80:83], v[138:141], v[226:229], v[80:83]
	v_mfma_f32_16x16x32_bf16 v[4:7], v[132:135], v[206:209], v[4:7]
	v_mfma_f32_16x16x32_bf16 v[0:3], v[142:145], v[206:209], v[0:3]
	v_mfma_f32_16x16x32_bf16 v[28:31], v[132:135], v[214:217], v[28:31]
	v_mfma_f32_16x16x32_bf16 v[24:27], v[142:145], v[214:217], v[24:27]
	v_mfma_f32_16x16x32_bf16 v[60:63], v[132:135], v[222:225], v[60:63]
	v_mfma_f32_16x16x32_bf16 v[56:59], v[142:145], v[222:225], v[56:59]
	v_mfma_f32_16x16x32_bf16 v[84:87], v[132:135], v[230:233], v[84:87]
	v_mfma_f32_16x16x32_bf16 v[80:83], v[142:145], v[230:233], v[80:83]
	s_setprio 0
	s_setprio 1
	v_mfma_f32_16x16x32_bf16 v[12:15], v[146:149], v[202:205], v[12:15]
	v_mfma_f32_16x16x32_bf16 v[8:11], v[158:161], v[202:205], v[8:11]
	v_mfma_f32_16x16x32_bf16 v[52:55], v[146:149], v[210:213], v[52:55]
	v_mfma_f32_16x16x32_bf16 v[48:51], v[158:161], v[210:213], v[48:51]
	v_mfma_f32_16x16x32_bf16 v[76:79], v[146:149], v[218:221], v[76:79]
	v_mfma_f32_16x16x32_bf16 v[72:75], v[158:161], v[218:221], v[72:75]
	v_mfma_f32_16x16x32_bf16 v[100:103], v[146:149], v[226:229], v[100:103]
	v_mfma_f32_16x16x32_bf16 v[96:99], v[158:161], v[226:229], v[96:99]
	v_mfma_f32_16x16x32_bf16 v[12:15], v[154:157], v[206:209], v[12:15]
	v_mfma_f32_16x16x32_bf16 v[8:11], v[198:201], v[206:209], v[8:11]
	v_mfma_f32_16x16x32_bf16 v[52:55], v[154:157], v[214:217], v[52:55]
	v_mfma_f32_16x16x32_bf16 v[48:51], v[198:201], v[214:217], v[48:51]
	v_mfma_f32_16x16x32_bf16 v[76:79], v[154:157], v[222:225], v[76:79]
	v_mfma_f32_16x16x32_bf16 v[72:75], v[198:201], v[222:225], v[72:75]
	v_mfma_f32_16x16x32_bf16 v[100:103], v[154:157], v[230:233], v[100:103]
	v_mfma_f32_16x16x32_bf16 v[96:99], v[198:201], v[230:233], v[96:99]
	s_setprio 0
	s_barrier
	v_add_u32_e32 v137, s53, v181
	s_mov_b32 m0, s39
	ds_read_b128 v[202:205], v191 offset:16384
	ds_read_b128 v[206:209], v191 offset:17408
	ds_read_b128 v[210:213], v191 offset:18432
	ds_read_b128 v[214:217], v191 offset:19456
	ds_read_b128 v[218:221], v191 offset:20480
	ds_read_b128 v[222:225], v191 offset:21504
	ds_read_b128 v[226:229], v191 offset:22528
	ds_read_b128 v[230:233], v191 offset:23552
	s_add_i32 s55, s53, 0x50000
	global_load_lds_dwordx4 v137, s[14:15]
	v_add_u32_e32 v137, s53, v183
	s_mov_b32 m0, s40
	s_nop 0
	global_load_lds_dwordx4 v137, s[14:15]
	v_add_u32_e32 v137, s55, v181
	s_mov_b32 m0, s41
	s_nop 0
	global_load_lds_dwordx4 v137, s[14:15]
	v_add_u32_e32 v137, s55, v183
	s_mov_b32 m0, s42
	s_nop 0
	global_load_lds_dwordx4 v137, s[14:15]
	v_add_u32_e32 v137, s54, v180
	s_mov_b32 m0, s23
	s_nop 0
	global_load_lds_dwordx4 v137, s[12:13]
	v_add_u32_e32 v137, s54, v182
	s_mov_b32 m0, s24
	s_nop 0
	global_load_lds_dwordx4 v137, s[12:13]
	s_waitcnt vmcnt(8)
	s_waitcnt lgkmcnt(0)
	s_barrier
	s_setprio 1
	s_waitcnt lgkmcnt(0)
	v_mfma_f32_16x16x32_bf16 v[116:119], v[36:39], v[202:205], v[116:119]
	v_mfma_f32_16x16x32_bf16 v[112:115], v[138:141], v[202:205], v[112:115]
	v_mfma_f32_16x16x32_bf16 v[128:131], v[36:39], v[210:213], v[128:131]
	v_mfma_f32_16x16x32_bf16 v[104:107], v[138:141], v[210:213], v[104:107]
	v_mfma_f32_16x16x32_bf16 v[68:71], v[36:39], v[218:221], v[68:71]
	v_mfma_f32_16x16x32_bf16 v[64:67], v[138:141], v[218:221], v[64:67]
	v_mfma_f32_16x16x32_bf16 v[32:35], v[138:141], v[226:229], v[32:35]
	v_mfma_f32_16x16x32_bf16 v[116:119], v[132:135], v[206:209], v[116:119]
	v_mfma_f32_16x16x32_bf16 v[112:115], v[142:145], v[206:209], v[112:115]
	v_mfma_f32_16x16x32_bf16 v[128:131], v[132:135], v[214:217], v[128:131]
	v_mfma_f32_16x16x32_bf16 v[104:107], v[142:145], v[214:217], v[104:107]
	v_mfma_f32_16x16x32_bf16 v[68:71], v[132:135], v[222:225], v[68:71]
	v_mfma_f32_16x16x32_bf16 v[64:67], v[142:145], v[222:225], v[64:67]
	v_mfma_f32_16x16x32_bf16 v[36:39], v[36:39], v[226:229], v[40:43]
	v_mfma_f32_16x16x32_bf16 v[32:35], v[142:145], v[230:233], v[32:35]
	v_mfma_f32_16x16x32_bf16 v[36:39], v[132:135], v[230:233], v[36:39]
	s_setprio 0
	s_setprio 1
	v_mfma_f32_16x16x32_bf16 v[40:43], v[146:149], v[202:205], v[124:127]
	v_mfma_f32_16x16x32_bf16 v[124:127], v[154:157], v[206:209], v[40:43]
	v_mfma_f32_16x16x32_bf16 v[40:43], v[158:161], v[202:205], v[120:123]
	v_mfma_f32_16x16x32_bf16 v[120:123], v[198:201], v[206:209], v[40:43]
	v_mfma_f32_16x16x32_bf16 v[40:43], v[146:149], v[210:213], v[108:111]
	v_mfma_f32_16x16x32_bf16 v[108:111], v[154:157], v[214:217], v[40:43]
	v_mfma_f32_16x16x32_bf16 v[40:43], v[158:161], v[210:213], v[88:91]
	v_mfma_f32_16x16x32_bf16 v[88:91], v[198:201], v[214:217], v[40:43]
	v_mfma_f32_16x16x32_bf16 v[40:43], v[146:149], v[218:221], v[92:95]
	v_mfma_f32_16x16x32_bf16 v[92:95], v[154:157], v[222:225], v[40:43]
	v_mfma_f32_16x16x32_bf16 v[40:43], v[158:161], v[218:221], v[44:47]
	v_mfma_f32_16x16x32_bf16 v[20:23], v[146:149], v[226:229], v[20:23]
	v_mfma_f32_16x16x32_bf16 v[16:19], v[158:161], v[226:229], v[16:19]
	v_mfma_f32_16x16x32_bf16 v[44:47], v[198:201], v[222:225], v[40:43]
	v_mfma_f32_16x16x32_bf16 v[20:23], v[154:157], v[230:233], v[20:23]
	v_mfma_f32_16x16x32_bf16 v[16:19], v[198:201], v[230:233], v[16:19]
	s_setprio 0
	s_barrier
;     ...
;         if constexpr (Epi::MIDHOOK) {
;             for (int t = 0; t < 4; t += 2) PG8_ITER(t);
;             E.mid(acc, cur, wr, wc, fr, fq);
;             for (int t = 4; t < nt; t += 2) PG8_ITER(t);
;         } else {
;             for (int t = 0; t < nt; t += 2) PG8_ITER(t);
	s_nop 0
	ds_read_b128 v[40:43], v167
	ds_read_b128 v[132:135], v167 offset:1024
	ds_read_b128 v[138:141], v167 offset:2048
	ds_read_b128 v[142:145], v167 offset:3072
	ds_read_b128 v[146:149], v169
	ds_read_b128 v[154:157], v169 offset:1024
	ds_read_b128 v[158:161], v169 offset:2048
	ds_read_b128 v[198:201], v169 offset:3072
	s_add_i32 s54, s54, 0x150000
	v_add_u32_e32 v137, s54, v180
	s_mov_b32 m0, s25
	ds_read_b128 v[202:205], v191 offset:32768
	ds_read_b128 v[206:209], v191 offset:33792
	ds_read_b128 v[210:213], v191 offset:34816
	ds_read_b128 v[214:217], v191 offset:35840
	ds_read_b128 v[218:221], v191 offset:36864
	ds_read_b128 v[222:225], v191 offset:37888
	ds_read_b128 v[226:229], v191 offset:38912
	ds_read_b128 v[230:233], v191 offset:39936
	s_nop 0
	global_load_lds_dwordx4 v137, s[12:13]
	v_add_u32_e32 v137, s54, v182
	s_mov_b32 m0, s26
	s_nop 0
	global_load_lds_dwordx4 v137, s[12:13]
	s_waitcnt vmcnt(8)
	s_waitcnt lgkmcnt(0)
	s_barrier
	s_setprio 1
	s_waitcnt lgkmcnt(0)
	v_mfma_f32_16x16x32_bf16 v[4:7], v[40:43], v[202:205], v[4:7]
	v_mfma_f32_16x16x32_bf16 v[0:3], v[138:141], v[202:205], v[0:3]
	v_mfma_f32_16x16x32_bf16 v[28:31], v[40:43], v[210:213], v[28:31]
	v_mfma_f32_16x16x32_bf16 v[24:27], v[138:141], v[210:213], v[24:27]
	v_mfma_f32_16x16x32_bf16 v[60:63], v[40:43], v[218:221], v[60:63]
	v_mfma_f32_16x16x32_bf16 v[56:59], v[138:141], v[218:221], v[56:59]
	v_mfma_f32_16x16x32_bf16 v[84:87], v[40:43], v[226:229], v[84:87]
	v_mfma_f32_16x16x32_bf16 v[80:83], v[138:141], v[226:229], v[80:83]
	v_mfma_f32_16x16x32_bf16 v[4:7], v[132:135], v[206:209], v[4:7]
	v_mfma_f32_16x16x32_bf16 v[0:3], v[142:145], v[206:209], v[0:3]
	v_mfma_f32_16x16x32_bf16 v[28:31], v[132:135], v[214:217], v[28:31]
	v_mfma_f32_16x16x32_bf16 v[24:27], v[142:145], v[214:217], v[24:27]
	v_mfma_f32_16x16x32_bf16 v[60:63], v[132:135], v[222:225], v[60:63]
	v_mfma_f32_16x16x32_bf16 v[56:59], v[142:145], v[222:225], v[56:59]
	v_mfma_f32_16x16x32_bf16 v[84:87], v[132:135], v[230:233], v[84:87]
	v_mfma_f32_16x16x32_bf16 v[80:83], v[142:145], v[230:233], v[80:83]
	s_setprio 0
	s_setprio 1
	v_mfma_f32_16x16x32_bf16 v[12:15], v[146:149], v[202:205], v[12:15]
	v_mfma_f32_16x16x32_bf16 v[8:11], v[158:161], v[202:205], v[8:11]
	v_mfma_f32_16x16x32_bf16 v[52:55], v[146:149], v[210:213], v[52:55]
	v_mfma_f32_16x16x32_bf16 v[48:51], v[158:161], v[210:213], v[48:51]
	v_mfma_f32_16x16x32_bf16 v[76:79], v[146:149], v[218:221], v[76:79]
	v_mfma_f32_16x16x32_bf16 v[72:75], v[158:161], v[218:221], v[72:75]
	v_mfma_f32_16x16x32_bf16 v[100:103], v[146:149], v[226:229], v[100:103]
	v_mfma_f32_16x16x32_bf16 v[96:99], v[158:161], v[226:229], v[96:99]
	v_mfma_f32_16x16x32_bf16 v[12:15], v[154:157], v[206:209], v[12:15]
	v_mfma_f32_16x16x32_bf16 v[8:11], v[198:201], v[206:209], v[8:11]
	v_mfma_f32_16x16x32_bf16 v[52:55], v[154:157], v[214:217], v[52:55]
	v_mfma_f32_16x16x32_bf16 v[48:51], v[198:201], v[214:217], v[48:51]
	v_mfma_f32_16x16x32_bf16 v[76:79], v[154:157], v[222:225], v[76:79]
	v_mfma_f32_16x16x32_bf16 v[72:75], v[198:201], v[222:225], v[72:75]
	v_mfma_f32_16x16x32_bf16 v[100:103], v[154:157], v[230:233], v[100:103]
	v_mfma_f32_16x16x32_bf16 v[96:99], v[198:201], v[230:233], v[96:99]
	s_setprio 0
	s_barrier
	s_or_b32 s54, s53, 0x80
	v_add_u32_e32 v137, s54, v181
	s_mov_b32 m0, s45
	ds_read_b128 v[202:205], v191 offset:49152
	ds_read_b128 v[206:209], v191 offset:50176
	ds_read_b128 v[210:213], v191 offset:51200
	ds_read_b128 v[214:217], v191 offset:52224
	ds_read_b128 v[218:221], v191 offset:53248
	ds_read_b128 v[222:225], v191 offset:54272
	ds_read_b128 v[226:229], v191 offset:55296
	ds_read_b128 v[230:233], v191 offset:56320
	s_add_i32 s53, s53, 0x50080
	global_load_lds_dwordx4 v137, s[14:15]
	v_add_u32_e32 v137, s54, v183
	s_mov_b32 m0, s46
	s_nop 0
	global_load_lds_dwordx4 v137, s[14:15]
	v_add_u32_e32 v137, s53, v181
	s_mov_b32 m0, s47
	s_nop 0
	global_load_lds_dwordx4 v137, s[14:15]
	v_add_u32_e32 v137, s53, v183
	s_mov_b32 m0, s48
	s_nop 0
	global_load_lds_dwordx4 v137, s[14:15]
	v_add_u32_e32 v137, s52, v180
	s_mov_b32 m0, s28
	s_nop 0
	global_load_lds_dwordx4 v137, s[12:13]
	v_add_u32_e32 v137, s52, v182
	s_mov_b32 m0, s29
	s_nop 0
	global_load_lds_dwordx4 v137, s[12:13]
	s_waitcnt vmcnt(8)
	s_waitcnt lgkmcnt(0)
	s_barrier
	s_setprio 1
	s_waitcnt lgkmcnt(0)
	v_mfma_f32_16x16x32_bf16 v[116:119], v[40:43], v[202:205], v[116:119]
	v_mfma_f32_16x16x32_bf16 v[112:115], v[138:141], v[202:205], v[112:115]
	v_mfma_f32_16x16x32_bf16 v[128:131], v[40:43], v[210:213], v[128:131]
	v_mfma_f32_16x16x32_bf16 v[104:107], v[138:141], v[210:213], v[104:107]
	v_mfma_f32_16x16x32_bf16 v[68:71], v[40:43], v[218:221], v[68:71]
	v_mfma_f32_16x16x32_bf16 v[64:67], v[138:141], v[218:221], v[64:67]
	v_mfma_f32_16x16x32_bf16 v[36:39], v[40:43], v[226:229], v[36:39]
	v_mfma_f32_16x16x32_bf16 v[32:35], v[138:141], v[226:229], v[32:35]
	v_mfma_f32_16x16x32_bf16 v[116:119], v[132:135], v[206:209], v[116:119]
	v_mfma_f32_16x16x32_bf16 v[112:115], v[142:145], v[206:209], v[112:115]
	v_mfma_f32_16x16x32_bf16 v[128:131], v[132:135], v[214:217], v[128:131]
	v_mfma_f32_16x16x32_bf16 v[104:107], v[142:145], v[214:217], v[104:107]
	v_mfma_f32_16x16x32_bf16 v[68:71], v[132:135], v[222:225], v[68:71]
	v_mfma_f32_16x16x32_bf16 v[64:67], v[142:145], v[222:225], v[64:67]
	v_mfma_f32_16x16x32_bf16 v[40:43], v[132:135], v[230:233], v[36:39]
	v_mfma_f32_16x16x32_bf16 v[32:35], v[142:145], v[230:233], v[32:35]
	s_setprio 0
	s_setprio 1
	v_mfma_f32_16x16x32_bf16 v[36:39], v[146:149], v[202:205], v[124:127]
	v_mfma_f32_16x16x32_bf16 v[124:127], v[154:157], v[206:209], v[36:39]
	v_mfma_f32_16x16x32_bf16 v[36:39], v[158:161], v[202:205], v[120:123]
	v_mfma_f32_16x16x32_bf16 v[120:123], v[198:201], v[206:209], v[36:39]
	v_mfma_f32_16x16x32_bf16 v[36:39], v[146:149], v[210:213], v[108:111]
	v_mfma_f32_16x16x32_bf16 v[108:111], v[154:157], v[214:217], v[36:39]
	v_mfma_f32_16x16x32_bf16 v[36:39], v[158:161], v[210:213], v[88:91]
	v_mfma_f32_16x16x32_bf16 v[88:91], v[198:201], v[214:217], v[36:39]
	v_mfma_f32_16x16x32_bf16 v[36:39], v[146:149], v[218:221], v[92:95]
	v_mfma_f32_16x16x32_bf16 v[92:95], v[154:157], v[222:225], v[36:39]
	v_mfma_f32_16x16x32_bf16 v[36:39], v[158:161], v[218:221], v[44:47]
	v_mfma_f32_16x16x32_bf16 v[20:23], v[146:149], v[226:229], v[20:23]
	v_mfma_f32_16x16x32_bf16 v[16:19], v[158:161], v[226:229], v[16:19]
	v_mfma_f32_16x16x32_bf16 v[44:47], v[198:201], v[222:225], v[36:39]
	v_mfma_f32_16x16x32_bf16 v[20:23], v[154:157], v[230:233], v[20:23]
	v_mfma_f32_16x16x32_bf16 v[16:19], v[198:201], v[230:233], v[16:19]
	s_setprio 0
	s_add_i32 s51, s51, 2
	s_addk_i32 s44, 0x100
	s_addk_i32 s43, 0x100
	s_cmp_gt_u32 s51, 17
	s_barrier
	s_cbranch_scc0 .LBB0_599
	s_and_b64 vcc, exec, s[20:21]
	s_cbranch_vccz .LBB0_602
	s_barrier

; #define PG8_STAGE(bufoff, goff, voff) do { _Pragma("unroll") for (int _i = 0; _i < 2; ++_i) { unsigned _vo = (voff)[_i] + (goff); asm volatile("" : "+v"(_vo)); \
;         __builtin_amdgcn_global_load_lds((const unsigned*)(base_##voff + _vo), (LAS unsigned*)(lds + (bufoff) + ldsw + _i * 8192), 16, 0, 0); } } while (0)
; #define PG8_WAIT_V(n) asm volatile("s_waitcnt vmcnt(" #n ")" ::: "memory")
; #define PG8_BAR __builtin_amdgcn_s_barrier()
;     ...
;     Unit cur, nxt; int ui = 0;
;     if (!S.next(0, cur)) return;
;     f32x4 acc[2][2][4][2];
; #pragma unroll
;     for (int a = 0; a < 2; ++a)
; #pragma unroll
;         for (int b = 0; b < 2; ++b)
; #pragma unroll
;             for (int m = 0; m < 4; ++m)
; #pragma unroll
;                 for (int n = 0; n < 2; ++n) acc[a][b][m][n] = (f32x4){0.f, 0.f, 0.f, 0.f};
;     bf16x8 At[4][2], B0[2][2], B1[2][2];
;     unsigned cA = (unsigned)cur.pm * tstepA, cB = (unsigned)cur.pn * tstepB;
;     PG8_STAGE(PG8_SB(0, 0), cB, voffB); PG8_STAGE(PG8_SB(0, 1), cB + hstepB, voffB); PG8_STAGE(PG8_SA(0, 0), cA + PG8_KOFFA(0), voffA); PG8_STAGE(PG8_SA(0, 1), cA + hstepA + PG8_KOFFA(0), voffA);
;     if (wr == 1) PG8_BAR;
;     PG8_WAIT_V(2); PG8_BAR;
;     PG8_STAGE(PG8_SB(1, 0), cB + kstep, voffB); PG8_STAGE(PG8_SA(1, 0), cA + PG8_KOFFA(1), voffA); PG8_STAGE(PG8_SB(1, 1), cB + hstepB + kstep, voffB);
;     PG8_WAIT_V(6); PG8_BAR;
;     for (;;) {
;         const bool has_next = S.next(ui + 1, nxt);
;         const unsigned nA = has_next ? (unsigned)nxt.pm * tstepA : cA, nB = has_next ? (unsigned)nxt.pn * tstepB : cB;
.LBB0_674:
	v_add_u32_e32 v154, s36, v136
	v_add_u32_e32 v170, s37, v136
	ds_read_b128 v[142:145], v154
	ds_read_b128 v[146:149], v154 offset:1024
	ds_read_b128 v[150:153], v154 offset:2048
	ds_read_b128 v[154:157], v154 offset:3072
	ds_read_b128 v[158:161], v170
	ds_read_b128 v[162:165], v170 offset:1024
	ds_read_b128 v[166:169], v170 offset:2048
	ds_read_b128 v[170:173], v170 offset:3072
	s_add_i32 s45, s28, s44
	s_add_i32 s46, s27, s44
	s_cmp_eq_u32 s43, 12
	s_cselect_b32 s47, s41, s45
	s_cselect_b32 s46, s42, s46
	s_or_b32 s45, s47, 0x80
	v_add_u32_e32 v185, s44, v141
	v_add_u32_e32 v185, 0x3ff80, v185
	ds_read_b128 v[174:177], v139
	ds_read_b128 v[178:181], v139 offset:1024
	ds_read_b128 v[192:195], v139 offset:2048
	ds_read_b128 v[196:199], v139 offset:3072
	ds_read_b128 v[200:203], v139 offset:4096
	ds_read_b128 v[204:207], v139 offset:5120
	ds_read_b128 v[208:211], v139 offset:6144
	ds_read_b128 v[212:215], v139 offset:7168
	s_add_i32 m0, s26, 0xc000
	s_nop 0
	global_load_lds_dwordx4 v185, s[10:11]
	v_add_u32_e32 v185, s44, v140
	v_add_u32_e32 v185, 0x3ff80, v185
	s_add_i32 m0, s26, 0xe000
	s_nop 0
	global_load_lds_dwordx4 v185, s[10:11]
	s_waitcnt vmcnt(8)
	s_waitcnt lgkmcnt(0)
	s_barrier
	s_setprio 1
	s_waitcnt lgkmcnt(0)
	v_mfma_f32_16x16x32_bf16 v[124:127], v[142:145], v[174:177], v[124:127]
	v_mfma_f32_16x16x32_bf16 v[120:123], v[150:153], v[174:177], v[120:123]
	v_mfma_f32_16x16x32_bf16 v[108:111], v[142:145], v[192:195], v[108:111]
	v_mfma_f32_16x16x32_bf16 v[104:107], v[150:153], v[192:195], v[104:107]
	v_mfma_f32_16x16x32_bf16 v[92:95], v[142:145], v[200:203], v[92:95]
	v_mfma_f32_16x16x32_bf16 v[88:91], v[150:153], v[200:203], v[88:91]
	v_mfma_f32_16x16x32_bf16 v[76:79], v[142:145], v[208:211], v[76:79]
	v_mfma_f32_16x16x32_bf16 v[72:75], v[150:153], v[208:211], v[72:75]
	v_mfma_f32_16x16x32_bf16 v[124:127], v[146:149], v[178:181], v[124:127]
	v_mfma_f32_16x16x32_bf16 v[120:123], v[154:157], v[178:181], v[120:123]
	v_mfma_f32_16x16x32_bf16 v[108:111], v[146:149], v[196:199], v[108:111]
	v_mfma_f32_16x16x32_bf16 v[104:107], v[154:157], v[196:199], v[104:107]
	v_mfma_f32_16x16x32_bf16 v[92:95], v[146:149], v[204:207], v[92:95]
	v_mfma_f32_16x16x32_bf16 v[88:91], v[154:157], v[204:207], v[88:91]
	v_mfma_f32_16x16x32_bf16 v[76:79], v[146:149], v[212:215], v[76:79]
	v_mfma_f32_16x16x32_bf16 v[72:75], v[154:157], v[212:215], v[72:75]
	s_setprio 0
	s_setprio 1
	v_mfma_f32_16x16x32_bf16 v[116:119], v[158:161], v[174:177], v[116:119]
	v_mfma_f32_16x16x32_bf16 v[112:115], v[166:169], v[174:177], v[112:115]
	v_mfma_f32_16x16x32_bf16 v[100:103], v[158:161], v[192:195], v[100:103]
	v_mfma_f32_16x16x32_bf16 v[96:99], v[166:169], v[192:195], v[96:99]
	v_mfma_f32_16x16x32_bf16 v[84:87], v[158:161], v[200:203], v[84:87]
	v_mfma_f32_16x16x32_bf16 v[80:83], v[166:169], v[200:203], v[80:83]
	v_mfma_f32_16x16x32_bf16 v[68:71], v[158:161], v[208:211], v[68:71]
	v_mfma_f32_16x16x32_bf16 v[64:67], v[166:169], v[208:211], v[64:67]
	v_mfma_f32_16x16x32_bf16 v[116:119], v[162:165], v[178:181], v[116:119]
	v_mfma_f32_16x16x32_bf16 v[112:115], v[170:173], v[178:181], v[112:115]
	v_mfma_f32_16x16x32_bf16 v[100:103], v[162:165], v[196:199], v[100:103]
	v_mfma_f32_16x16x32_bf16 v[96:99], v[170:173], v[196:199], v[96:99]
	v_mfma_f32_16x16x32_bf16 v[84:87], v[162:165], v[204:207], v[84:87]
	v_mfma_f32_16x16x32_bf16 v[80:83], v[170:173], v[204:207], v[80:83]
	v_mfma_f32_16x16x32_bf16 v[68:71], v[162:165], v[212:215], v[68:71]
	v_mfma_f32_16x16x32_bf16 v[64:67], v[170:173], v[212:215], v[64:67]
	s_setprio 0
	s_barrier
	v_add_u32_e32 v185, s46, v133
	s_add_i32 s48, s36, s25
	ds_read_b128 v[174:177], v139 offset:16384
	ds_read_b128 v[178:181], v139 offset:17408
	ds_read_b128 v[192:195], v139 offset:18432
	ds_read_b128 v[196:199], v139 offset:19456
	ds_read_b128 v[200:203], v139 offset:20480
	ds_read_b128 v[204:207], v139 offset:21504
	ds_read_b128 v[208:211], v139 offset:22528
	ds_read_b128 v[212:215], v139 offset:23552
	s_mov_b32 m0, s48
	s_add_i32 s49, s37, s25
	global_load_lds_dwordx4 v185, s[0:1]
	v_add_u32_e32 v185, s46, v135
	s_add_i32 m0, s48, 0x2000
	s_add_i32 s48, s46, 0x40000
	global_load_lds_dwordx4 v185, s[0:1]
	v_add_u32_e32 v185, s48, v133
	s_mov_b32 m0, s49
	s_nop 0
	global_load_lds_dwordx4 v185, s[0:1]
	v_add_u32_e32 v185, s48, v135
	s_add_i32 m0, s49, 0x2000
	s_nop 0
	global_load_lds_dwordx4 v185, s[0:1]
	v_add_u32_e32 v185, s47, v132
	s_mov_b32 m0, s26
	s_nop 0
	global_load_lds_dwordx4 v185, s[10:11]
	v_add_u32_e32 v185, s47, v134
	s_mov_b32 m0, s29
	s_nop 0
	global_load_lds_dwordx4 v185, s[10:11]
	s_waitcnt vmcnt(8)
	s_waitcnt lgkmcnt(0)
	s_barrier
; #define PG8_STAGE(bufoff, goff, voff) do { _Pragma("unroll") for (int _i = 0; _i < 2; ++_i) { unsigned _vo = (voff)[_i] + (goff); asm volatile("" : "+v"(_vo)); \
;         __builtin_amdgcn_global_load_lds((const unsigned*)(base_##voff + _vo), (LAS unsigned*)(lds + (bufoff) + ldsw + _i * 8192), 16, 0, 0); } } while (0)
; #define PG8_WAIT_V(n) asm volatile("s_waitcnt vmcnt(" #n ")" ::: "memory")
; #define PG8_BAR __builtin_amdgcn_s_barrier()
;     ...
;     Unit cur, nxt; int ui = 0;
;     if (!S.next(0, cur)) return;
;     f32x4 acc[2][2][4][2];
; #pragma unroll
;     for (int a = 0; a < 2; ++a)
; #pragma unroll
;         for (int b = 0; b < 2; ++b)
; #pragma unroll
;             for (int m = 0; m < 4; ++m)
; #pragma unroll
;                 for (int n = 0; n < 2; ++n) acc[a][b][m][n] = (f32x4){0.f, 0.f, 0.f, 0.f};
;     bf16x8 At[4][2], B0[2][2], B1[2][2];
;     unsigned cA = (unsigned)cur.pm * tstepA, cB = (unsigned)cur.pn * tstepB;
;     PG8_STAGE(PG8_SB(0, 0), cB, voffB); PG8_STAGE(PG8_SB(0, 1), cB + hstepB, voffB); PG8_STAGE(PG8_SA(0, 0), cA + PG8_KOFFA(0), voffA); PG8_STAGE(PG8_SA(0, 1), cA + hstepA + PG8_KOFFA(0), voffA);
;     if (wr == 1) PG8_BAR;
;     PG8_WAIT_V(2); PG8_BAR;
;     PG8_STAGE(PG8_SB(1, 0), cB + kstep, voffB); PG8_STAGE(PG8_SA(1, 0), cA + PG8_KOFFA(1), voffA); PG8_STAGE(PG8_SB(1, 1), cB + hstepB + kstep, voffB);
;     PG8_WAIT_V(6); PG8_BAR;
;     for (;;) {
;         const bool has_next = S.next(ui + 1, nxt);
;         const unsigned nA = has_next ? (unsigned)nxt.pm * tstepA : cA, nB = has_next ? (unsigned)nxt.pn * tstepB : cB;
	s_setprio 1
	s_waitcnt lgkmcnt(0)
	v_mfma_f32_16x16x32_bf16 v[60:63], v[142:145], v[174:177], v[60:63]
	v_mfma_f32_16x16x32_bf16 v[56:59], v[150:153], v[174:177], v[56:59]
	v_mfma_f32_16x16x32_bf16 v[44:47], v[142:145], v[192:195], v[44:47]
	v_mfma_f32_16x16x32_bf16 v[40:43], v[150:153], v[192:195], v[40:43]
	v_mfma_f32_16x16x32_bf16 v[28:31], v[142:145], v[200:203], v[28:31]
	v_mfma_f32_16x16x32_bf16 v[24:27], v[150:153], v[200:203], v[24:27]
	v_mfma_f32_16x16x32_bf16 v[12:15], v[142:145], v[208:211], v[12:15]
	v_mfma_f32_16x16x32_bf16 v[8:11], v[150:153], v[208:211], v[8:11]
	v_mfma_f32_16x16x32_bf16 v[60:63], v[146:149], v[178:181], v[60:63]
	v_mfma_f32_16x16x32_bf16 v[56:59], v[154:157], v[178:181], v[56:59]
	v_mfma_f32_16x16x32_bf16 v[44:47], v[146:149], v[196:199], v[44:47]
	v_mfma_f32_16x16x32_bf16 v[40:43], v[154:157], v[196:199], v[40:43]
	v_mfma_f32_16x16x32_bf16 v[28:31], v[146:149], v[204:207], v[28:31]
	v_mfma_f32_16x16x32_bf16 v[24:27], v[154:157], v[204:207], v[24:27]
	v_mfma_f32_16x16x32_bf16 v[12:15], v[146:149], v[212:215], v[12:15]
	v_mfma_f32_16x16x32_bf16 v[8:11], v[154:157], v[212:215], v[8:11]
	s_setprio 0
	s_setprio 1
	v_mfma_f32_16x16x32_bf16 v[52:55], v[158:161], v[174:177], v[52:55]
	v_mfma_f32_16x16x32_bf16 v[48:51], v[166:169], v[174:177], v[48:51]
	v_mfma_f32_16x16x32_bf16 v[36:39], v[158:161], v[192:195], v[36:39]
	v_mfma_f32_16x16x32_bf16 v[32:35], v[166:169], v[192:195], v[32:35]
	v_mfma_f32_16x16x32_bf16 v[20:23], v[158:161], v[200:203], v[20:23]
	v_mfma_f32_16x16x32_bf16 v[16:19], v[166:169], v[200:203], v[16:19]
	v_mfma_f32_16x16x32_bf16 v[4:7], v[158:161], v[208:211], v[4:7]
	v_mfma_f32_16x16x32_bf16 v[0:3], v[166:169], v[208:211], v[0:3]
	v_mfma_f32_16x16x32_bf16 v[52:55], v[162:165], v[178:181], v[52:55]
	v_mfma_f32_16x16x32_bf16 v[48:51], v[170:173], v[178:181], v[48:51]
	v_mfma_f32_16x16x32_bf16 v[36:39], v[162:165], v[196:199], v[36:39]
	v_mfma_f32_16x16x32_bf16 v[32:35], v[170:173], v[196:199], v[32:35]
	v_mfma_f32_16x16x32_bf16 v[20:23], v[162:165], v[204:207], v[20:23]
	v_mfma_f32_16x16x32_bf16 v[16:19], v[170:173], v[204:207], v[16:19]
	v_mfma_f32_16x16x32_bf16 v[4:7], v[162:165], v[212:215], v[4:7]
	v_mfma_f32_16x16x32_bf16 v[0:3], v[170:173], v[212:215], v[0:3]
	s_setprio 0
	s_barrier
	s_add_i32 s48, 0, 0x18000
	s_add_i32 s49, 0, 0x1c000
	v_add_u32_e32 v154, s48, v136
	v_add_u32_e32 v170, s49, v136
	ds_read_b128 v[142:145], v154
	ds_read_b128 v[146:149], v154 offset:1024
	ds_read_b128 v[150:153], v154 offset:2048
	ds_read_b128 v[154:157], v154 offset:3072
	ds_read_b128 v[158:161], v170
	ds_read_b128 v[162:165], v170 offset:1024
	ds_read_b128 v[166:169], v170 offset:2048
	ds_read_b128 v[170:173], v170 offset:3072
	s_add_i32 s47, s47, 0x40000
	v_add_u32_e32 v185, s47, v132
	s_mov_b32 m0, s30
	ds_read_b128 v[174:177], v139 offset:32768
	ds_read_b128 v[178:181], v139 offset:33792
	ds_read_b128 v[192:195], v139 offset:34816
	ds_read_b128 v[196:199], v139 offset:35840
	ds_read_b128 v[200:203], v139 offset:36864
	ds_read_b128 v[204:207], v139 offset:37888
	ds_read_b128 v[208:211], v139 offset:38912
	ds_read_b128 v[212:215], v139 offset:39936
	s_nop 0
	global_load_lds_dwordx4 v185, s[10:11]
	v_add_u32_e32 v185, s47, v134
	s_mov_b32 m0, s31
	s_nop 0
	global_load_lds_dwordx4 v185, s[10:11]
	s_waitcnt vmcnt(8)
	s_waitcnt lgkmcnt(0)
	s_barrier
	s_setprio 1
	s_waitcnt lgkmcnt(0)
	v_mfma_f32_16x16x32_bf16 v[124:127], v[142:145], v[174:177], v[124:127]
	v_mfma_f32_16x16x32_bf16 v[120:123], v[150:153], v[174:177], v[120:123]
	v_mfma_f32_16x16x32_bf16 v[108:111], v[142:145], v[192:195], v[108:111]
	v_mfma_f32_16x16x32_bf16 v[104:107], v[150:153], v[192:195], v[104:107]
	v_mfma_f32_16x16x32_bf16 v[92:95], v[142:145], v[200:203], v[92:95]
	v_mfma_f32_16x16x32_bf16 v[88:91], v[150:153], v[200:203], v[88:91]
	v_mfma_f32_16x16x32_bf16 v[76:79], v[142:145], v[208:211], v[76:79]
	v_mfma_f32_16x16x32_bf16 v[72:75], v[150:153], v[208:211], v[72:75]
	v_mfma_f32_16x16x32_bf16 v[124:127], v[146:149], v[178:181], v[124:127]
	v_mfma_f32_16x16x32_bf16 v[120:123], v[154:157], v[178:181], v[120:123]
	v_mfma_f32_16x16x32_bf16 v[108:111], v[146:149], v[196:199], v[108:111]
	v_mfma_f32_16x16x32_bf16 v[104:107], v[154:157], v[196:199], v[104:107]
	v_mfma_f32_16x16x32_bf16 v[92:95], v[146:149], v[204:207], v[92:95]
	v_mfma_f32_16x16x32_bf16 v[88:91], v[154:157], v[204:207], v[88:91]
	v_mfma_f32_16x16x32_bf16 v[76:79], v[146:149], v[212:215], v[76:79]
	v_mfma_f32_16x16x32_bf16 v[72:75], v[154:157], v[212:215], v[72:75]
	s_setprio 0
	s_setprio 1
	v_mfma_f32_16x16x32_bf16 v[116:119], v[158:161], v[174:177], v[116:119]
	v_mfma_f32_16x16x32_bf16 v[112:115], v[166:169], v[174:177], v[112:115]
	v_mfma_f32_16x16x32_bf16 v[100:103], v[158:161], v[192:195], v[100:103]
	v_mfma_f32_16x16x32_bf16 v[96:99], v[166:169], v[192:195], v[96:99]
	v_mfma_f32_16x16x32_bf16 v[84:87], v[158:161], v[200:203], v[84:87]
	v_mfma_f32_16x16x32_bf16 v[80:83], v[166:169], v[200:203], v[80:83]
	v_mfma_f32_16x16x32_bf16 v[68:71], v[158:161], v[208:211], v[68:71]
	v_mfma_f32_16x16x32_bf16 v[64:67], v[166:169], v[208:211], v[64:67]
	v_mfma_f32_16x16x32_bf16 v[116:119], v[162:165], v[178:181], v[116:119]
	v_mfma_f32_16x16x32_bf16 v[112:115], v[170:173], v[178:181], v[112:115]
	v_mfma_f32_16x16x32_bf16 v[100:103], v[162:165], v[196:199], v[100:103]
	v_mfma_f32_16x16x32_bf16 v[96:99], v[170:173], v[196:199], v[96:99]
	v_mfma_f32_16x16x32_bf16 v[84:87], v[162:165], v[204:207], v[84:87]
	v_mfma_f32_16x16x32_bf16 v[80:83], v[170:173], v[204:207], v[80:83]
	v_mfma_f32_16x16x32_bf16 v[68:71], v[162:165], v[212:215], v[68:71]
	v_mfma_f32_16x16x32_bf16 v[64:67], v[170:173], v[212:215], v[64:67]
	s_setprio 0
	s_barrier
; #define PG8_BAR __builtin_amdgcn_s_barrier()
;     ...
;         if constexpr (Epi::MIDHOOK) {
;             for (int t = 0; t < 4; t += 2) PG8_ITER(t);
;             E.mid(acc, cur, wr, wc, fr, fq);
;             for (int t = 4; t < nt; t += 2) PG8_ITER(t);
;         } else {
;             for (int t = 0; t < nt; t += 2) PG8_ITER(t);
;         }
;     ...
;         if constexpr (ALIGN_EPI) { if (wr == 0) PG8_BAR; }
;         if constexpr (!Epi::AFTER_DRAIN) { E(acc, cur, wr, wc, fr, fq); }
;         if (!has_next) break;
; #pragma unroll
;         for (int a = 0; a < 2; ++a)
; #pragma unroll
;             for (int b = 0; b < 2; ++b)
; #pragma unroll
;                 for (int m = 0; m < 4; ++m)
; #pragma unroll
;                     for (int n = 0; n < 2; ++n) acc[a][b][m][n] = (f32x4){0.f, 0.f, 0.f, 0.f};
;         cur = nxt; cA = nA; cB = nB; ++ui;
	s_or_b32 s47, s46, 0x80
	v_add_u32_e32 v185, s47, v133
	s_add_i32 s48, s48, s25
	ds_read_b128 v[174:177], v139 offset:49152
	ds_read_b128 v[178:181], v139 offset:50176
	ds_read_b128 v[192:195], v139 offset:51200
	ds_read_b128 v[196:199], v139 offset:52224
	ds_read_b128 v[200:203], v139 offset:53248
	ds_read_b128 v[204:207], v139 offset:54272
	ds_read_b128 v[208:211], v139 offset:55296
	ds_read_b128 v[212:215], v139 offset:56320
	s_mov_b32 m0, s48
	s_add_i32 s46, s46, 0x40080
	global_load_lds_dwordx4 v185, s[0:1]
	v_add_u32_e32 v185, s47, v135
	s_add_i32 m0, s48, 0x2000
	s_add_i32 s47, s49, s25
	global_load_lds_dwordx4 v185, s[0:1]
	v_add_u32_e32 v185, s46, v133
	s_mov_b32 m0, s47
	s_nop 0
	global_load_lds_dwordx4 v185, s[0:1]
	v_add_u32_e32 v185, s46, v135
	s_add_i32 m0, s47, 0x2000
	s_nop 0
	global_load_lds_dwordx4 v185, s[0:1]
	v_add_u32_e32 v185, s45, v132
	s_mov_b32 m0, s33
	s_nop 0
	global_load_lds_dwordx4 v185, s[10:11]
	v_add_u32_e32 v185, s45, v134
	s_mov_b32 m0, s34
	s_nop 0
	global_load_lds_dwordx4 v185, s[10:11]
	s_waitcnt vmcnt(8)
	s_waitcnt lgkmcnt(0)
	s_barrier
	s_setprio 1
	s_waitcnt lgkmcnt(0)
	v_mfma_f32_16x16x32_bf16 v[60:63], v[142:145], v[174:177], v[60:63]
	v_mfma_f32_16x16x32_bf16 v[56:59], v[150:153], v[174:177], v[56:59]
	v_mfma_f32_16x16x32_bf16 v[44:47], v[142:145], v[192:195], v[44:47]
	v_mfma_f32_16x16x32_bf16 v[40:43], v[150:153], v[192:195], v[40:43]
	v_mfma_f32_16x16x32_bf16 v[28:31], v[142:145], v[200:203], v[28:31]
	v_mfma_f32_16x16x32_bf16 v[24:27], v[150:153], v[200:203], v[24:27]
	v_mfma_f32_16x16x32_bf16 v[12:15], v[142:145], v[208:211], v[12:15]
	v_mfma_f32_16x16x32_bf16 v[8:11], v[150:153], v[208:211], v[8:11]
	v_mfma_f32_16x16x32_bf16 v[60:63], v[146:149], v[178:181], v[60:63]
	v_mfma_f32_16x16x32_bf16 v[56:59], v[154:157], v[178:181], v[56:59]
	v_mfma_f32_16x16x32_bf16 v[44:47], v[146:149], v[196:199], v[44:47]
	v_mfma_f32_16x16x32_bf16 v[40:43], v[154:157], v[196:199], v[40:43]
	v_mfma_f32_16x16x32_bf16 v[28:31], v[146:149], v[204:207], v[28:31]
	v_mfma_f32_16x16x32_bf16 v[24:27], v[154:157], v[204:207], v[24:27]
	v_mfma_f32_16x16x32_bf16 v[12:15], v[146:149], v[212:215], v[12:15]
	v_mfma_f32_16x16x32_bf16 v[8:11], v[154:157], v[212:215], v[8:11]
	s_setprio 0
	s_setprio 1
	v_mfma_f32_16x16x32_bf16 v[52:55], v[158:161], v[174:177], v[52:55]
	v_mfma_f32_16x16x32_bf16 v[48:51], v[166:169], v[174:177], v[48:51]
	v_mfma_f32_16x16x32_bf16 v[36:39], v[158:161], v[192:195], v[36:39]
	v_mfma_f32_16x16x32_bf16 v[32:35], v[166:169], v[192:195], v[32:35]
	v_mfma_f32_16x16x32_bf16 v[20:23], v[158:161], v[200:203], v[20:23]
	v_mfma_f32_16x16x32_bf16 v[16:19], v[166:169], v[200:203], v[16:19]
	v_mfma_f32_16x16x32_bf16 v[4:7], v[158:161], v[208:211], v[4:7]
	v_mfma_f32_16x16x32_bf16 v[0:3], v[166:169], v[208:211], v[0:3]
	v_mfma_f32_16x16x32_bf16 v[52:55], v[162:165], v[178:181], v[52:55]
	v_mfma_f32_16x16x32_bf16 v[48:51], v[170:173], v[178:181], v[48:51]
	v_mfma_f32_16x16x32_bf16 v[36:39], v[162:165], v[196:199], v[36:39]
	v_mfma_f32_16x16x32_bf16 v[32:35], v[170:173], v[196:199], v[32:35]
	v_mfma_f32_16x16x32_bf16 v[20:23], v[162:165], v[204:207], v[20:23]
	v_mfma_f32_16x16x32_bf16 v[16:19], v[170:173], v[204:207], v[16:19]
	v_mfma_f32_16x16x32_bf16 v[4:7], v[162:165], v[212:215], v[4:7]
	v_mfma_f32_16x16x32_bf16 v[0:3], v[170:173], v[212:215], v[0:3]
	s_setprio 0
	s_add_i32 s43, s43, 2
	s_addk_i32 s44, 0x100
	s_cmp_gt_u32 s43, 13
	s_barrier
	s_cbranch_scc0 .LBB0_674
	s_andn2_b64 vcc, exec, s[8:9]
	s_cbranch_vccnz .LBB0_666
	v_mov_b32_e32 v0, 0
	s_mov_b32 s16, s38
	s_mov_b32 s21, s39
	s_mov_b32 s27, s3
	s_mov_b32 s28, s2
	s_mov_b32 s35, s40
	v_mov_b32_e32 v1, v0
	v_mov_b32_e32 v2, v0
	v_mov_b32_e32 v3, v0
	v_mov_b32_e32 v4, v0
	v_mov_b32_e32 v5, v0
	v_mov_b32_e32 v6, v0
	v_mov_b32_e32 v7, v0
	v_mov_b32_e32 v16, v0
	v_mov_b32_e32 v17, v0
	v_mov_b32_e32 v18, v0
	v_mov_b32_e32 v19, v0
	v_mov_b32_e32 v20, v0
	v_mov_b32_e32 v21, v0
	v_mov_b32_e32 v22, v0
	v_mov_b32_e32 v23, v0
	v_mov_b32_e32 v32, v0
	v_mov_b32_e32 v33, v0
	v_mov_b32_e32 v34, v0
	v_mov_b32_e32 v35, v0
	v_mov_b32_e32 v36, v0
	v_mov_b32_e32 v37, v0
	v_mov_b32_e32 v38, v0
	v_mov_b32_e32 v39, v0
	v_mov_b32_e32 v48, v0
	v_mov_b32_e32 v49, v0
	v_mov_b32_e32 v50, v0
	v_mov_b32_e32 v51, v0
	v_mov_b32_e32 v52, v0
	v_mov_b32_e32 v53, v0
	v_mov_b32_e32 v54, v0
	v_mov_b32_e32 v55, v0
	v_mov_b32_e32 v8, v0
	v_mov_b32_e32 v9, v0
	v_mov_b32_e32 v10, v0
	v_mov_b32_e32 v11, v0
	v_mov_b32_e32 v12, v0
	v_mov_b32_e32 v13, v0
	v_mov_b32_e32 v14, v0
	v_mov_b32_e32 v15, v0
	v_mov_b32_e32 v24, v0
	v_mov_b32_e32 v25, v0
	v_mov_b32_e32 v26, v0
	v_mov_b32_e32 v27, v0
	v_mov_b32_e32 v28, v0
	v_mov_b32_e32 v29, v0
	v_mov_b32_e32 v30, v0
	v_mov_b32_e32 v31, v0
	v_mov_b32_e32 v40, v0
	v_mov_b32_e32 v41, v0
	v_mov_b32_e32 v42, v0
	v_mov_b32_e32 v43, v0
	v_mov_b32_e32 v44, v0
	v_mov_b32_e32 v45, v0
	v_mov_b32_e32 v46, v0
	v_mov_b32_e32 v47, v0
	v_mov_b32_e32 v56, v0
	v_mov_b32_e32 v57, v0
	v_mov_b32_e32 v58, v0
	v_mov_b32_e32 v59, v0
	v_mov_b32_e32 v60, v0
	v_mov_b32_e32 v61, v0
	v_mov_b32_e32 v62, v0
	v_mov_b32_e32 v63, v0
	v_mov_b32_e32 v64, v0
	v_mov_b32_e32 v65, v0
	v_mov_b32_e32 v66, v0
	v_mov_b32_e32 v67, v0
	v_mov_b32_e32 v68, v0
	v_mov_b32_e32 v69, v0
	v_mov_b32_e32 v70, v0
	v_mov_b32_e32 v71, v0
	v_mov_b32_e32 v80, v0
	v_mov_b32_e32 v81, v0
	v_mov_b32_e32 v82, v0
	v_mov_b32_e32 v83, v0
	v_mov_b32_e32 v84, v0
	v_mov_b32_e32 v85, v0
	v_mov_b32_e32 v86, v0
	v_mov_b32_e32 v87, v0
	v_mov_b32_e32 v96, v0
	v_mov_b32_e32 v97, v0
	v_mov_b32_e32 v98, v0
	v_mov_b32_e32 v99, v0
	v_mov_b32_e32 v100, v0
	v_mov_b32_e32 v101, v0
	v_mov_b32_e32 v102, v0
	v_mov_b32_e32 v103, v0
	v_mov_b32_e32 v112, v0
	v_mov_b32_e32 v113, v0
	v_mov_b32_e32 v114, v0
	v_mov_b32_e32 v115, v0
	v_mov_b32_e32 v116, v0
	v_mov_b32_e32 v117, v0
	v_mov_b32_e32 v118, v0
	v_mov_b32_e32 v119, v0
	v_mov_b32_e32 v72, v0
	v_mov_b32_e32 v73, v0
	v_mov_b32_e32 v74, v0
	v_mov_b32_e32 v75, v0
	v_mov_b32_e32 v76, v0
	v_mov_b32_e32 v77, v0
	v_mov_b32_e32 v78, v0
	v_mov_b32_e32 v79, v0
	v_mov_b32_e32 v88, v0
	v_mov_b32_e32 v89, v0
	v_mov_b32_e32 v90, v0
	v_mov_b32_e32 v91, v0
	v_mov_b32_e32 v92, v0
	v_mov_b32_e32 v93, v0
	v_mov_b32_e32 v94, v0
	v_mov_b32_e32 v95, v0
	v_mov_b32_e32 v104, v0
	v_mov_b32_e32 v105, v0
	v_mov_b32_e32 v106, v0
	v_mov_b32_e32 v107, v0
	v_mov_b32_e32 v108, v0
	v_mov_b32_e32 v109, v0
	v_mov_b32_e32 v110, v0
	v_mov_b32_e32 v111, v0
	v_mov_b32_e32 v120, v0
	v_mov_b32_e32 v121, v0
	v_mov_b32_e32 v122, v0
	v_mov_b32_e32 v123, v0
	v_mov_b32_e32 v124, v0
	v_mov_b32_e32 v125, v0
	v_mov_b32_e32 v126, v0
	v_mov_b32_e32 v127, v0
	s_branch .LBB0_666

; #define PG8_STAGE(bufoff, goff, voff) do { _Pragma("unroll") for (int _i = 0; _i < 2; ++_i) { unsigned _vo = (voff)[_i] + (goff); asm volatile("" : "+v"(_vo)); \
;         __builtin_amdgcn_global_load_lds((const unsigned*)(base_##voff + _vo), (LAS unsigned*)(lds + (bufoff) + ldsw + _i * 8192), 16, 0, 0); } } while (0)
; #define PG8_WAIT_V(n) asm volatile("s_waitcnt vmcnt(" #n ")" ::: "memory")
; #define PG8_BAR __builtin_amdgcn_s_barrier()
;     ...
;     Unit cur, nxt; int ui = 0;
;     if (!S.next(0, cur)) return;
;     f32x4 acc[2][2][4][2];
; #pragma unroll
;     for (int a = 0; a < 2; ++a)
; #pragma unroll
;         for (int b = 0; b < 2; ++b)
; #pragma unroll
;             for (int m = 0; m < 4; ++m)
; #pragma unroll
;                 for (int n = 0; n < 2; ++n) acc[a][b][m][n] = (f32x4){0.f, 0.f, 0.f, 0.f};
;     bf16x8 At[4][2], B0[2][2], B1[2][2];
;     unsigned cA = (unsigned)cur.pm * tstepA, cB = (unsigned)cur.pn * tstepB;
;     PG8_STAGE(PG8_SB(0, 0), cB, voffB); PG8_STAGE(PG8_SB(0, 1), cB + hstepB, voffB); PG8_STAGE(PG8_SA(0, 0), cA + PG8_KOFFA(0), voffA); PG8_STAGE(PG8_SA(0, 1), cA + hstepA + PG8_KOFFA(0), voffA);
;     if (wr == 1) PG8_BAR;
;     PG8_WAIT_V(2); PG8_BAR;
;     PG8_STAGE(PG8_SB(1, 0), cB + kstep, voffB); PG8_STAGE(PG8_SA(1, 0), cA + PG8_KOFFA(1), voffA); PG8_STAGE(PG8_SB(1, 1), cB + hstepB + kstep, voffB);
;     PG8_WAIT_V(6); PG8_BAR;
;     for (;;) {
;         const bool has_next = S.next(ui + 1, nxt);
;         const unsigned nA = has_next ? (unsigned)nxt.pm * tstepA : cA, nB = has_next ? (unsigned)nxt.pn * tstepB : cB;
.LBB0_780:
	ds_read_b128 v[128:131], v207
	ds_read_b128 v[132:135], v207 offset:1024
	ds_read_b128 v[136:139], v207 offset:2048
	ds_read_b128 v[140:143], v207 offset:3072
	ds_read_b128 v[144:147], v208
	ds_read_b128 v[148:151], v208 offset:1024
	ds_read_b128 v[152:155], v208 offset:2048
	ds_read_b128 v[156:159], v208 offset:3072
	s_add_i32 s12, s2, 0xffffe080
	s_cmp_eq_u32 s11, 12
	s_cselect_b32 s14, s0, s12
	s_cselect_b32 s13, s1, s3
	s_or_b32 s12, s14, 0x80
	v_add_u32_e32 v184, s2, v206
	ds_read_b128 v[164:167], v209
	ds_read_b128 v[168:171], v209 offset:1024
	ds_read_b128 v[172:175], v209 offset:2048
	ds_read_b128 v[176:179], v209 offset:3072
	ds_read_b128 v[180:183], v209 offset:4096
	ds_read_b128 v[210:213], v209 offset:5120
	ds_read_b128 v[214:217], v209 offset:6144
	ds_read_b128 v[218:221], v209 offset:7168
	s_add_i32 m0, s27, 0xc000
	s_nop 0
	global_load_lds_dwordx4 v184, s[22:23]
	v_add_u32_e32 v184, s2, v205
	s_add_i32 m0, s27, 0xe000
	s_nop 0
	global_load_lds_dwordx4 v184, s[22:23]
	s_waitcnt vmcnt(8)
	s_waitcnt lgkmcnt(0)
	s_barrier
	s_setprio 1
	s_waitcnt lgkmcnt(0)
	v_mfma_f32_16x16x32_bf16 v[120:123], v[128:131], v[164:167], v[120:123]
	v_mfma_f32_16x16x32_bf16 v[56:59], v[136:139], v[164:167], v[56:59]
	v_mfma_f32_16x16x32_bf16 v[112:115], v[128:131], v[172:175], v[112:115]
	v_mfma_f32_16x16x32_bf16 v[48:51], v[136:139], v[172:175], v[48:51]
	v_mfma_f32_16x16x32_bf16 v[104:107], v[128:131], v[180:183], v[104:107]
	v_mfma_f32_16x16x32_bf16 v[40:43], v[136:139], v[180:183], v[40:43]
	v_mfma_f32_16x16x32_bf16 v[96:99], v[128:131], v[214:217], v[96:99]
	v_mfma_f32_16x16x32_bf16 v[32:35], v[136:139], v[214:217], v[32:35]
	v_mfma_f32_16x16x32_bf16 v[120:123], v[132:135], v[168:171], v[120:123]
	v_mfma_f32_16x16x32_bf16 v[56:59], v[140:143], v[168:171], v[56:59]
	v_mfma_f32_16x16x32_bf16 v[112:115], v[132:135], v[176:179], v[112:115]
	v_mfma_f32_16x16x32_bf16 v[48:51], v[140:143], v[176:179], v[48:51]
	v_mfma_f32_16x16x32_bf16 v[104:107], v[132:135], v[210:213], v[104:107]
	v_mfma_f32_16x16x32_bf16 v[40:43], v[140:143], v[210:213], v[40:43]
	v_mfma_f32_16x16x32_bf16 v[96:99], v[132:135], v[218:221], v[96:99]
	v_mfma_f32_16x16x32_bf16 v[32:35], v[140:143], v[218:221], v[32:35]
	s_setprio 0
	s_setprio 1
	v_mfma_f32_16x16x32_bf16 v[124:127], v[144:147], v[164:167], v[124:127]
	v_mfma_f32_16x16x32_bf16 v[60:63], v[152:155], v[164:167], v[60:63]
	v_mfma_f32_16x16x32_bf16 v[116:119], v[144:147], v[172:175], v[116:119]
	v_mfma_f32_16x16x32_bf16 v[52:55], v[152:155], v[172:175], v[52:55]
	v_mfma_f32_16x16x32_bf16 v[108:111], v[144:147], v[180:183], v[108:111]
	v_mfma_f32_16x16x32_bf16 v[44:47], v[152:155], v[180:183], v[44:47]
	v_mfma_f32_16x16x32_bf16 v[100:103], v[144:147], v[214:217], v[100:103]
	v_mfma_f32_16x16x32_bf16 v[36:39], v[152:155], v[214:217], v[36:39]
	v_mfma_f32_16x16x32_bf16 v[124:127], v[148:151], v[168:171], v[124:127]
	v_mfma_f32_16x16x32_bf16 v[60:63], v[156:159], v[168:171], v[60:63]
	v_mfma_f32_16x16x32_bf16 v[116:119], v[148:151], v[176:179], v[116:119]
	v_mfma_f32_16x16x32_bf16 v[52:55], v[156:159], v[176:179], v[52:55]
	v_mfma_f32_16x16x32_bf16 v[108:111], v[148:151], v[210:213], v[108:111]
	v_mfma_f32_16x16x32_bf16 v[44:47], v[156:159], v[210:213], v[44:47]
	v_mfma_f32_16x16x32_bf16 v[100:103], v[148:151], v[218:221], v[100:103]
	v_mfma_f32_16x16x32_bf16 v[36:39], v[156:159], v[218:221], v[36:39]
	s_setprio 0
	s_barrier
	v_add_u32_e32 v184, s13, v192
	s_add_i32 s15, s71, s26
	ds_read_b128 v[164:167], v209 offset:16384
	ds_read_b128 v[168:171], v209 offset:17408
	ds_read_b128 v[172:175], v209 offset:18432
	ds_read_b128 v[176:179], v209 offset:19456
	ds_read_b128 v[180:183], v209 offset:20480
	ds_read_b128 v[210:213], v209 offset:21504
	ds_read_b128 v[214:217], v209 offset:22528
	ds_read_b128 v[218:221], v209 offset:23552
	s_mov_b32 m0, s15
	s_add_i32 s16, s72, s26
	global_load_lds_dwordx4 v184, s[36:37]
	v_add_u32_e32 v184, s13, v194
	s_add_i32 m0, s15, 0x2000
	s_add_i32 s15, s13, 0x40000
	global_load_lds_dwordx4 v184, s[36:37]
	v_add_u32_e32 v184, s15, v192
	s_mov_b32 m0, s16
	s_nop 0
	global_load_lds_dwordx4 v184, s[36:37]
	v_add_u32_e32 v184, s15, v194
	s_add_i32 m0, s16, 0x2000
	s_nop 0
	global_load_lds_dwordx4 v184, s[36:37]
	v_add_u32_e32 v184, s14, v191
	s_mov_b32 m0, s27
	s_nop 0
	global_load_lds_dwordx4 v184, s[22:23]
	v_add_u32_e32 v184, s14, v193
	s_mov_b32 m0, s33
	s_nop 0
	global_load_lds_dwordx4 v184, s[22:23]
	s_waitcnt vmcnt(8)
	s_waitcnt lgkmcnt(0)
	s_barrier
	s_setprio 1
	s_waitcnt lgkmcnt(0)
	v_mfma_f32_16x16x32_bf16 v[88:91], v[128:131], v[164:167], v[88:91]
	v_mfma_f32_16x16x32_bf16 v[24:27], v[136:139], v[164:167], v[24:27]
	v_mfma_f32_16x16x32_bf16 v[72:75], v[128:131], v[172:175], v[72:75]
	v_mfma_f32_16x16x32_bf16 v[8:11], v[136:139], v[172:175], v[8:11]
	v_mfma_f32_16x16x32_bf16 v[68:71], v[128:131], v[180:183], v[68:71]
	v_mfma_f32_16x16x32_bf16 v[4:7], v[136:139], v[180:183], v[4:7]
	v_mfma_f32_16x16x32_bf16 v[64:67], v[128:131], v[214:217], v[64:67]
	v_mfma_f32_16x16x32_bf16 v[0:3], v[136:139], v[214:217], v[0:3]
	v_mfma_f32_16x16x32_bf16 v[88:91], v[132:135], v[168:171], v[88:91]
	v_mfma_f32_16x16x32_bf16 v[24:27], v[140:143], v[168:171], v[24:27]
	v_mfma_f32_16x16x32_bf16 v[72:75], v[132:135], v[176:179], v[72:75]
	v_mfma_f32_16x16x32_bf16 v[8:11], v[140:143], v[176:179], v[8:11]
	v_mfma_f32_16x16x32_bf16 v[68:71], v[132:135], v[210:213], v[68:71]
	v_mfma_f32_16x16x32_bf16 v[4:7], v[140:143], v[210:213], v[4:7]
	v_mfma_f32_16x16x32_bf16 v[64:67], v[132:135], v[218:221], v[64:67]
	v_mfma_f32_16x16x32_bf16 v[0:3], v[140:143], v[218:221], v[0:3]
	s_setprio 0
	s_setprio 1
	v_mfma_f32_16x16x32_bf16 v[92:95], v[144:147], v[164:167], v[92:95]
	v_mfma_f32_16x16x32_bf16 v[28:31], v[152:155], v[164:167], v[28:31]
	v_mfma_f32_16x16x32_bf16 v[76:79], v[144:147], v[172:175], v[76:79]
	v_mfma_f32_16x16x32_bf16 v[16:19], v[152:155], v[172:175], v[16:19]
	v_mfma_f32_16x16x32_bf16 v[84:87], v[144:147], v[180:183], v[84:87]
	v_mfma_f32_16x16x32_bf16 v[20:23], v[152:155], v[180:183], v[20:23]
	v_mfma_f32_16x16x32_bf16 v[80:83], v[144:147], v[214:217], v[80:83]
	v_mfma_f32_16x16x32_bf16 v[12:15], v[152:155], v[214:217], v[12:15]
	v_mfma_f32_16x16x32_bf16 v[92:95], v[148:151], v[168:171], v[92:95]
	v_mfma_f32_16x16x32_bf16 v[28:31], v[156:159], v[168:171], v[28:31]
	v_mfma_f32_16x16x32_bf16 v[76:79], v[148:151], v[176:179], v[76:79]
	v_mfma_f32_16x16x32_bf16 v[16:19], v[156:159], v[176:179], v[16:19]
	v_mfma_f32_16x16x32_bf16 v[84:87], v[148:151], v[210:213], v[84:87]
	v_mfma_f32_16x16x32_bf16 v[20:23], v[156:159], v[210:213], v[20:23]
	v_mfma_f32_16x16x32_bf16 v[80:83], v[148:151], v[218:221], v[80:83]
	v_mfma_f32_16x16x32_bf16 v[12:15], v[156:159], v[218:221], v[12:15]
	s_setprio 0
	s_barrier
;     ...
;         if constexpr (Epi::MIDHOOK) {
;             for (int t = 0; t < 4; t += 2) PG8_ITER(t);
;             E.mid(acc, cur, wr, wc, fr, fq);
;             for (int t = 4; t < nt; t += 2) PG8_ITER(t);
;         } else {
;             for (int t = 0; t < nt; t += 2) PG8_ITER(t);
	s_add_i32 s15, 0, 0x18000
	s_add_i32 s16, 0, 0x1c000
	v_add_u32_e32 v140, s15, v195
	v_add_u32_e32 v156, s16, v195
	ds_read_b128 v[128:131], v140
	ds_read_b128 v[132:135], v140 offset:1024
	ds_read_b128 v[136:139], v140 offset:2048
	ds_read_b128 v[140:143], v140 offset:3072
	ds_read_b128 v[144:147], v156
	ds_read_b128 v[148:151], v156 offset:1024
	ds_read_b128 v[152:155], v156 offset:2048
	ds_read_b128 v[156:159], v156 offset:3072
	s_addk_i32 s14, 0x2000
	v_add_u32_e32 v184, s14, v191
	s_mov_b32 m0, s34
	ds_read_b128 v[164:167], v209 offset:32768
	ds_read_b128 v[168:171], v209 offset:33792
	ds_read_b128 v[172:175], v209 offset:34816
	ds_read_b128 v[176:179], v209 offset:35840
	ds_read_b128 v[180:183], v209 offset:36864
	ds_read_b128 v[210:213], v209 offset:37888
	ds_read_b128 v[214:217], v209 offset:38912
	ds_read_b128 v[218:221], v209 offset:39936
	s_nop 0
	global_load_lds_dwordx4 v184, s[22:23]
	v_add_u32_e32 v184, s14, v193
	s_mov_b32 m0, s35
	s_nop 0
	global_load_lds_dwordx4 v184, s[22:23]
	s_waitcnt vmcnt(8)
	s_waitcnt lgkmcnt(0)
	s_barrier
	s_setprio 1
	s_waitcnt lgkmcnt(0)
	v_mfma_f32_16x16x32_bf16 v[120:123], v[128:131], v[164:167], v[120:123]
	v_mfma_f32_16x16x32_bf16 v[56:59], v[136:139], v[164:167], v[56:59]
	v_mfma_f32_16x16x32_bf16 v[112:115], v[128:131], v[172:175], v[112:115]
	v_mfma_f32_16x16x32_bf16 v[48:51], v[136:139], v[172:175], v[48:51]
	v_mfma_f32_16x16x32_bf16 v[104:107], v[128:131], v[180:183], v[104:107]
	v_mfma_f32_16x16x32_bf16 v[40:43], v[136:139], v[180:183], v[40:43]
	v_mfma_f32_16x16x32_bf16 v[96:99], v[128:131], v[214:217], v[96:99]
	v_mfma_f32_16x16x32_bf16 v[32:35], v[136:139], v[214:217], v[32:35]
	v_mfma_f32_16x16x32_bf16 v[120:123], v[132:135], v[168:171], v[120:123]
	v_mfma_f32_16x16x32_bf16 v[56:59], v[140:143], v[168:171], v[56:59]
	v_mfma_f32_16x16x32_bf16 v[112:115], v[132:135], v[176:179], v[112:115]
	v_mfma_f32_16x16x32_bf16 v[48:51], v[140:143], v[176:179], v[48:51]
	v_mfma_f32_16x16x32_bf16 v[104:107], v[132:135], v[210:213], v[104:107]
	v_mfma_f32_16x16x32_bf16 v[40:43], v[140:143], v[210:213], v[40:43]
	v_mfma_f32_16x16x32_bf16 v[96:99], v[132:135], v[218:221], v[96:99]
	v_mfma_f32_16x16x32_bf16 v[32:35], v[140:143], v[218:221], v[32:35]
	s_setprio 0
	s_setprio 1
	v_mfma_f32_16x16x32_bf16 v[124:127], v[144:147], v[164:167], v[124:127]
	v_mfma_f32_16x16x32_bf16 v[60:63], v[152:155], v[164:167], v[60:63]
	v_mfma_f32_16x16x32_bf16 v[116:119], v[144:147], v[172:175], v[116:119]
	v_mfma_f32_16x16x32_bf16 v[52:55], v[152:155], v[172:175], v[52:55]
	v_mfma_f32_16x16x32_bf16 v[108:111], v[144:147], v[180:183], v[108:111]
	v_mfma_f32_16x16x32_bf16 v[44:47], v[152:155], v[180:183], v[44:47]
	v_mfma_f32_16x16x32_bf16 v[100:103], v[144:147], v[214:217], v[100:103]
	v_mfma_f32_16x16x32_bf16 v[36:39], v[152:155], v[214:217], v[36:39]
	v_mfma_f32_16x16x32_bf16 v[124:127], v[148:151], v[168:171], v[124:127]
	v_mfma_f32_16x16x32_bf16 v[60:63], v[156:159], v[168:171], v[60:63]
	v_mfma_f32_16x16x32_bf16 v[116:119], v[148:151], v[176:179], v[116:119]
	v_mfma_f32_16x16x32_bf16 v[52:55], v[156:159], v[176:179], v[52:55]
	v_mfma_f32_16x16x32_bf16 v[108:111], v[148:151], v[210:213], v[108:111]
	v_mfma_f32_16x16x32_bf16 v[44:47], v[156:159], v[210:213], v[44:47]
	v_mfma_f32_16x16x32_bf16 v[100:103], v[148:151], v[218:221], v[100:103]
	v_mfma_f32_16x16x32_bf16 v[36:39], v[156:159], v[218:221], v[36:39]
	s_setprio 0
	s_barrier
	s_or_b32 s14, s13, 0x80
	v_add_u32_e32 v184, s14, v192
	s_add_i32 s15, s15, s26
	ds_read_b128 v[164:167], v209 offset:49152
	ds_read_b128 v[168:171], v209 offset:50176
	ds_read_b128 v[172:175], v209 offset:51200
	ds_read_b128 v[176:179], v209 offset:52224
	ds_read_b128 v[180:183], v209 offset:53248
	ds_read_b128 v[210:213], v209 offset:54272
	ds_read_b128 v[214:217], v209 offset:55296
	ds_read_b128 v[218:221], v209 offset:56320
	s_mov_b32 m0, s15
	s_add_i32 s13, s13, 0x40080
	global_load_lds_dwordx4 v184, s[36:37]
	v_add_u32_e32 v184, s14, v194
	s_add_i32 m0, s15, 0x2000
	s_add_i32 s14, s16, s26
	global_load_lds_dwordx4 v184, s[36:37]
	v_add_u32_e32 v184, s13, v192
	s_mov_b32 m0, s14
	s_nop 0
	global_load_lds_dwordx4 v184, s[36:37]
	v_add_u32_e32 v184, s13, v194
	s_add_i32 m0, s14, 0x2000
	s_nop 0
	global_load_lds_dwordx4 v184, s[36:37]
	v_add_u32_e32 v184, s12, v191
	s_mov_b32 m0, s61
	s_nop 0
	global_load_lds_dwordx4 v184, s[22:23]
	v_add_u32_e32 v184, s12, v193
	s_mov_b32 m0, s63
	s_nop 0
	global_load_lds_dwordx4 v184, s[22:23]
	s_waitcnt vmcnt(8)
	s_waitcnt lgkmcnt(0)
	s_barrier
	s_setprio 1
	s_waitcnt lgkmcnt(0)
	v_mfma_f32_16x16x32_bf16 v[88:91], v[128:131], v[164:167], v[88:91]
	v_mfma_f32_16x16x32_bf16 v[24:27], v[136:139], v[164:167], v[24:27]
	v_mfma_f32_16x16x32_bf16 v[72:75], v[128:131], v[172:175], v[72:75]
	v_mfma_f32_16x16x32_bf16 v[8:11], v[136:139], v[172:175], v[8:11]
	v_mfma_f32_16x16x32_bf16 v[68:71], v[128:131], v[180:183], v[68:71]
	v_mfma_f32_16x16x32_bf16 v[4:7], v[136:139], v[180:183], v[4:7]
	v_mfma_f32_16x16x32_bf16 v[64:67], v[128:131], v[214:217], v[64:67]
	v_mfma_f32_16x16x32_bf16 v[0:3], v[136:139], v[214:217], v[0:3]
	v_mfma_f32_16x16x32_bf16 v[88:91], v[132:135], v[168:171], v[88:91]
	v_mfma_f32_16x16x32_bf16 v[24:27], v[140:143], v[168:171], v[24:27]
	v_mfma_f32_16x16x32_bf16 v[72:75], v[132:135], v[176:179], v[72:75]
	v_mfma_f32_16x16x32_bf16 v[8:11], v[140:143], v[176:179], v[8:11]
	v_mfma_f32_16x16x32_bf16 v[68:71], v[132:135], v[210:213], v[68:71]
	v_mfma_f32_16x16x32_bf16 v[4:7], v[140:143], v[210:213], v[4:7]
	v_mfma_f32_16x16x32_bf16 v[64:67], v[132:135], v[218:221], v[64:67]
	v_mfma_f32_16x16x32_bf16 v[0:3], v[140:143], v[218:221], v[0:3]
	s_setprio 0
	s_setprio 1
	v_mfma_f32_16x16x32_bf16 v[92:95], v[144:147], v[164:167], v[92:95]
	v_mfma_f32_16x16x32_bf16 v[28:31], v[152:155], v[164:167], v[28:31]
	v_mfma_f32_16x16x32_bf16 v[76:79], v[144:147], v[172:175], v[76:79]
	v_mfma_f32_16x16x32_bf16 v[16:19], v[152:155], v[172:175], v[16:19]
	v_mfma_f32_16x16x32_bf16 v[84:87], v[144:147], v[180:183], v[84:87]
	v_mfma_f32_16x16x32_bf16 v[20:23], v[152:155], v[180:183], v[20:23]
	v_mfma_f32_16x16x32_bf16 v[80:83], v[144:147], v[214:217], v[80:83]
	v_mfma_f32_16x16x32_bf16 v[12:15], v[152:155], v[214:217], v[12:15]
	v_mfma_f32_16x16x32_bf16 v[92:95], v[148:151], v[168:171], v[92:95]
	v_mfma_f32_16x16x32_bf16 v[28:31], v[156:159], v[168:171], v[28:31]
	v_mfma_f32_16x16x32_bf16 v[76:79], v[148:151], v[176:179], v[76:79]
	v_mfma_f32_16x16x32_bf16 v[16:19], v[156:159], v[176:179], v[16:19]
	v_mfma_f32_16x16x32_bf16 v[84:87], v[148:151], v[210:213], v[84:87]
	v_mfma_f32_16x16x32_bf16 v[20:23], v[156:159], v[210:213], v[20:23]
	v_mfma_f32_16x16x32_bf16 v[80:83], v[148:151], v[218:221], v[80:83]
	v_mfma_f32_16x16x32_bf16 v[12:15], v[156:159], v[218:221], v[12:15]
	s_setprio 0
	s_add_i32 s11, s11, 2
	s_addk_i32 s2, 0x100
	s_addk_i32 s3, 0x100
	s_cmp_gt_u32 s11, 13
	s_barrier
	s_cbranch_scc0 .LBB0_780
	s_and_b64 vcc, exec, s[42:43]
	s_cbranch_vccz .LBB0_783
	s_barrier

; #define PG8_STAGE(bufoff, goff, voff) do { _Pragma("unroll") for (int _i = 0; _i < 2; ++_i) { unsigned _vo = (voff)[_i] + (goff); asm volatile("" : "+v"(_vo)); \
;         __builtin_amdgcn_global_load_lds((const unsigned*)(base_##voff + _vo), (LAS unsigned*)(lds + (bufoff) + ldsw + _i * 8192), 16, 0, 0); } } while (0)
; #define PG8_WAIT_V(n) asm volatile("s_waitcnt vmcnt(" #n ")" ::: "memory")
; #define PG8_BAR __builtin_amdgcn_s_barrier()
;     ...
;     Unit cur, nxt; int ui = 0;
;     if (!S.next(0, cur)) return;
;     f32x4 acc[2][2][4][2];
; #pragma unroll
;     for (int a = 0; a < 2; ++a)
; #pragma unroll
;         for (int b = 0; b < 2; ++b)
; #pragma unroll
;             for (int m = 0; m < 4; ++m)
; #pragma unroll
;                 for (int n = 0; n < 2; ++n) acc[a][b][m][n] = (f32x4){0.f, 0.f, 0.f, 0.f};
;     bf16x8 At[4][2], B0[2][2], B1[2][2];
;     unsigned cA = (unsigned)cur.pm * tstepA, cB = (unsigned)cur.pn * tstepB;
;     PG8_STAGE(PG8_SB(0, 0), cB, voffB); PG8_STAGE(PG8_SB(0, 1), cB + hstepB, voffB); PG8_STAGE(PG8_SA(0, 0), cA + PG8_KOFFA(0), voffA); PG8_STAGE(PG8_SA(0, 1), cA + hstepA + PG8_KOFFA(0), voffA);
;     if (wr == 1) PG8_BAR;
;     PG8_WAIT_V(2); PG8_BAR;
;     PG8_STAGE(PG8_SB(1, 0), cB + kstep, voffB); PG8_STAGE(PG8_SA(1, 0), cA + PG8_KOFFA(1), voffA); PG8_STAGE(PG8_SB(1, 1), cB + hstepB + kstep, voffB);
;     PG8_WAIT_V(6); PG8_BAR;
;     for (;;) {
;         const bool has_next = S.next(ui + 1, nxt);
;         const unsigned nA = has_next ? (unsigned)nxt.pm * tstepA : cA, nB = has_next ? (unsigned)nxt.pn * tstepB : cB;
.LBB0_924:
	v_add_u32_e32 v154, s34, v136
	v_add_u32_e32 v162, s35, v136
	ds_read_b128 v[142:145], v154
	ds_read_b128 v[146:149], v154 offset:1024
	ds_read_b128 v[150:153], v154 offset:2048
	ds_read_b128 v[154:157], v154 offset:3072
	ds_read_b128 v[158:161], v162
	ds_read_b128 v[166:169], v162 offset:1024
	ds_read_b128 v[170:173], v162 offset:2048
	ds_read_b128 v[174:177], v162 offset:3072
	s_add_i32 s43, s46, 0x100
	s_add_i32 s44, s43, s26
	s_add_i32 s45, s39, s46
	s_cmpk_eq_i32 s46, 0x1500
	s_cselect_b32 s47, s40, s44
	s_cselect_b32 s45, s41, s45
	s_or_b32 s44, s47, 0x80
	v_add_u32_e32 v162, s46, v141
	ds_read_b128 v[178:181], v139
	ds_read_b128 v[182:185], v139 offset:1024
	ds_read_b128 v[192:195], v139 offset:2048
	ds_read_b128 v[196:199], v139 offset:3072
	ds_read_b128 v[200:203], v139 offset:4096
	ds_read_b128 v[204:207], v139 offset:5120
	ds_read_b128 v[208:211], v139 offset:6144
	ds_read_b128 v[212:215], v139 offset:7168
	s_add_i32 m0, s24, 0xc000
	s_nop 0
	global_load_lds_dwordx4 v162, s[2:3]
	v_add_u32_e32 v162, s46, v140
	s_add_i32 m0, s24, 0xe000
	s_nop 0
	global_load_lds_dwordx4 v162, s[2:3]
	s_waitcnt vmcnt(8)
	s_waitcnt lgkmcnt(0)
	s_barrier
	s_setprio 1
	s_waitcnt lgkmcnt(0)
	v_mfma_f32_16x16x32_bf16 v[124:127], v[142:145], v[178:181], v[124:127]
	v_mfma_f32_16x16x32_bf16 v[120:123], v[150:153], v[178:181], v[120:123]
	v_mfma_f32_16x16x32_bf16 v[108:111], v[142:145], v[192:195], v[108:111]
	v_mfma_f32_16x16x32_bf16 v[104:107], v[150:153], v[192:195], v[104:107]
	v_mfma_f32_16x16x32_bf16 v[92:95], v[142:145], v[200:203], v[92:95]
	v_mfma_f32_16x16x32_bf16 v[88:91], v[150:153], v[200:203], v[88:91]
	v_mfma_f32_16x16x32_bf16 v[76:79], v[142:145], v[208:211], v[76:79]
	v_mfma_f32_16x16x32_bf16 v[72:75], v[150:153], v[208:211], v[72:75]
	v_mfma_f32_16x16x32_bf16 v[124:127], v[146:149], v[182:185], v[124:127]
	v_mfma_f32_16x16x32_bf16 v[120:123], v[154:157], v[182:185], v[120:123]
	v_mfma_f32_16x16x32_bf16 v[108:111], v[146:149], v[196:199], v[108:111]
	v_mfma_f32_16x16x32_bf16 v[104:107], v[154:157], v[196:199], v[104:107]
	v_mfma_f32_16x16x32_bf16 v[92:95], v[146:149], v[204:207], v[92:95]
	v_mfma_f32_16x16x32_bf16 v[88:91], v[154:157], v[204:207], v[88:91]
	v_mfma_f32_16x16x32_bf16 v[76:79], v[146:149], v[212:215], v[76:79]
	v_mfma_f32_16x16x32_bf16 v[72:75], v[154:157], v[212:215], v[72:75]
	s_setprio 0
	s_setprio 1
	v_mfma_f32_16x16x32_bf16 v[116:119], v[158:161], v[178:181], v[116:119]
	v_mfma_f32_16x16x32_bf16 v[112:115], v[170:173], v[178:181], v[112:115]
	v_mfma_f32_16x16x32_bf16 v[100:103], v[158:161], v[192:195], v[100:103]
	v_mfma_f32_16x16x32_bf16 v[96:99], v[170:173], v[192:195], v[96:99]
	v_mfma_f32_16x16x32_bf16 v[84:87], v[158:161], v[200:203], v[84:87]
	v_mfma_f32_16x16x32_bf16 v[80:83], v[170:173], v[200:203], v[80:83]
	v_mfma_f32_16x16x32_bf16 v[68:71], v[158:161], v[208:211], v[68:71]
	v_mfma_f32_16x16x32_bf16 v[64:67], v[170:173], v[208:211], v[64:67]
	v_mfma_f32_16x16x32_bf16 v[116:119], v[166:169], v[182:185], v[116:119]
	v_mfma_f32_16x16x32_bf16 v[112:115], v[174:177], v[182:185], v[112:115]
	v_mfma_f32_16x16x32_bf16 v[100:103], v[166:169], v[196:199], v[100:103]
	v_mfma_f32_16x16x32_bf16 v[96:99], v[174:177], v[196:199], v[96:99]
	v_mfma_f32_16x16x32_bf16 v[84:87], v[166:169], v[204:207], v[84:87]
	v_mfma_f32_16x16x32_bf16 v[80:83], v[174:177], v[204:207], v[80:83]
	v_mfma_f32_16x16x32_bf16 v[68:71], v[166:169], v[212:215], v[68:71]
	v_mfma_f32_16x16x32_bf16 v[64:67], v[174:177], v[212:215], v[64:67]
	s_setprio 0
	s_barrier
	v_add_u32_e32 v162, s45, v133
	s_add_i32 s46, s34, s23
	ds_read_b128 v[178:181], v139 offset:16384
	ds_read_b128 v[182:185], v139 offset:17408
	ds_read_b128 v[192:195], v139 offset:18432
	ds_read_b128 v[196:199], v139 offset:19456
	ds_read_b128 v[200:203], v139 offset:20480
	ds_read_b128 v[204:207], v139 offset:21504
	ds_read_b128 v[208:211], v139 offset:22528
	ds_read_b128 v[212:215], v139 offset:23552
	s_mov_b32 m0, s46
	s_add_i32 s48, s35, s23
	global_load_lds_dwordx4 v162, s[14:15]
	v_add_u32_e32 v162, s45, v135
	s_add_i32 m0, s46, 0x2000
	s_add_i32 s46, s45, 0xb0000
	global_load_lds_dwordx4 v162, s[14:15]
	v_add_u32_e32 v162, s46, v133
	s_mov_b32 m0, s48
	s_nop 0
	global_load_lds_dwordx4 v162, s[14:15]
	v_add_u32_e32 v162, s46, v135
	s_add_i32 m0, s48, 0x2000
	s_nop 0
	global_load_lds_dwordx4 v162, s[14:15]
	v_add_u32_e32 v162, s47, v132
	s_mov_b32 m0, s24
	s_nop 0
	global_load_lds_dwordx4 v162, s[2:3]
	v_add_u32_e32 v162, s47, v134
	s_mov_b32 m0, s27
	s_nop 0
	global_load_lds_dwordx4 v162, s[2:3]
	s_waitcnt vmcnt(8)
	s_waitcnt lgkmcnt(0)
	s_barrier
	s_setprio 1
	s_waitcnt lgkmcnt(0)
	v_mfma_f32_16x16x32_bf16 v[60:63], v[142:145], v[178:181], v[60:63]
	v_mfma_f32_16x16x32_bf16 v[56:59], v[150:153], v[178:181], v[56:59]
	v_mfma_f32_16x16x32_bf16 v[44:47], v[142:145], v[192:195], v[44:47]
	v_mfma_f32_16x16x32_bf16 v[40:43], v[150:153], v[192:195], v[40:43]
	v_mfma_f32_16x16x32_bf16 v[28:31], v[142:145], v[200:203], v[28:31]
	v_mfma_f32_16x16x32_bf16 v[24:27], v[150:153], v[200:203], v[24:27]
	v_mfma_f32_16x16x32_bf16 v[12:15], v[142:145], v[208:211], v[12:15]
	v_mfma_f32_16x16x32_bf16 v[8:11], v[150:153], v[208:211], v[8:11]
	v_mfma_f32_16x16x32_bf16 v[60:63], v[146:149], v[182:185], v[60:63]
	v_mfma_f32_16x16x32_bf16 v[56:59], v[154:157], v[182:185], v[56:59]
	v_mfma_f32_16x16x32_bf16 v[44:47], v[146:149], v[196:199], v[44:47]
	v_mfma_f32_16x16x32_bf16 v[40:43], v[154:157], v[196:199], v[40:43]
	v_mfma_f32_16x16x32_bf16 v[28:31], v[146:149], v[204:207], v[28:31]
	v_mfma_f32_16x16x32_bf16 v[24:27], v[154:157], v[204:207], v[24:27]
	v_mfma_f32_16x16x32_bf16 v[12:15], v[146:149], v[212:215], v[12:15]
	v_mfma_f32_16x16x32_bf16 v[8:11], v[154:157], v[212:215], v[8:11]
	s_setprio 0
	s_setprio 1
	v_mfma_f32_16x16x32_bf16 v[52:55], v[158:161], v[178:181], v[52:55]
	v_mfma_f32_16x16x32_bf16 v[48:51], v[170:173], v[178:181], v[48:51]
	v_mfma_f32_16x16x32_bf16 v[36:39], v[158:161], v[192:195], v[36:39]
	v_mfma_f32_16x16x32_bf16 v[32:35], v[170:173], v[192:195], v[32:35]
	v_mfma_f32_16x16x32_bf16 v[20:23], v[158:161], v[200:203], v[20:23]
	v_mfma_f32_16x16x32_bf16 v[16:19], v[170:173], v[200:203], v[16:19]
	v_mfma_f32_16x16x32_bf16 v[4:7], v[158:161], v[208:211], v[4:7]
	v_mfma_f32_16x16x32_bf16 v[0:3], v[170:173], v[208:211], v[0:3]
	v_mfma_f32_16x16x32_bf16 v[52:55], v[166:169], v[182:185], v[52:55]
	v_mfma_f32_16x16x32_bf16 v[48:51], v[174:177], v[182:185], v[48:51]
	v_mfma_f32_16x16x32_bf16 v[36:39], v[166:169], v[196:199], v[36:39]
	v_mfma_f32_16x16x32_bf16 v[32:35], v[174:177], v[196:199], v[32:35]
	v_mfma_f32_16x16x32_bf16 v[20:23], v[166:169], v[204:207], v[20:23]
	v_mfma_f32_16x16x32_bf16 v[16:19], v[174:177], v[204:207], v[16:19]
	v_mfma_f32_16x16x32_bf16 v[4:7], v[166:169], v[212:215], v[4:7]
	v_mfma_f32_16x16x32_bf16 v[0:3], v[174:177], v[212:215], v[0:3]
	s_setprio 0
	s_barrier
	s_add_i32 s46, 0, 0x18000
	s_add_i32 s48, 0, 0x1c000
	v_add_u32_e32 v154, s46, v136
	v_add_u32_e32 v162, s48, v136
	ds_read_b128 v[142:145], v154
	ds_read_b128 v[146:149], v154 offset:1024
	ds_read_b128 v[150:153], v154 offset:2048
	ds_read_b128 v[154:157], v154 offset:3072
	ds_read_b128 v[158:161], v162
	ds_read_b128 v[166:169], v162 offset:1024
	ds_read_b128 v[170:173], v162 offset:2048
	ds_read_b128 v[174:177], v162 offset:3072
	s_add_i32 s47, s47, 0xb0000
	v_add_u32_e32 v162, s47, v132
	s_mov_b32 m0, s28
	ds_read_b128 v[178:181], v139 offset:32768
	ds_read_b128 v[182:185], v139 offset:33792
	ds_read_b128 v[192:195], v139 offset:34816
	ds_read_b128 v[196:199], v139 offset:35840
	ds_read_b128 v[200:203], v139 offset:36864
	ds_read_b128 v[204:207], v139 offset:37888
	ds_read_b128 v[208:211], v139 offset:38912
	ds_read_b128 v[212:215], v139 offset:39936
	s_nop 0
	global_load_lds_dwordx4 v162, s[2:3]
	v_add_u32_e32 v162, s47, v134
	s_mov_b32 m0, s29
	s_nop 0
	global_load_lds_dwordx4 v162, s[2:3]
	s_waitcnt vmcnt(8)
	s_waitcnt lgkmcnt(0)
	s_barrier
	s_setprio 1
	s_waitcnt lgkmcnt(0)
	v_mfma_f32_16x16x32_bf16 v[124:127], v[142:145], v[178:181], v[124:127]
	v_mfma_f32_16x16x32_bf16 v[120:123], v[150:153], v[178:181], v[120:123]
	v_mfma_f32_16x16x32_bf16 v[108:111], v[142:145], v[192:195], v[108:111]
	v_mfma_f32_16x16x32_bf16 v[104:107], v[150:153], v[192:195], v[104:107]
	v_mfma_f32_16x16x32_bf16 v[92:95], v[142:145], v[200:203], v[92:95]
	v_mfma_f32_16x16x32_bf16 v[88:91], v[150:153], v[200:203], v[88:91]
	v_mfma_f32_16x16x32_bf16 v[76:79], v[142:145], v[208:211], v[76:79]
	v_mfma_f32_16x16x32_bf16 v[72:75], v[150:153], v[208:211], v[72:75]
	v_mfma_f32_16x16x32_bf16 v[124:127], v[146:149], v[182:185], v[124:127]
	v_mfma_f32_16x16x32_bf16 v[120:123], v[154:157], v[182:185], v[120:123]
	v_mfma_f32_16x16x32_bf16 v[108:111], v[146:149], v[196:199], v[108:111]
	v_mfma_f32_16x16x32_bf16 v[104:107], v[154:157], v[196:199], v[104:107]
	v_mfma_f32_16x16x32_bf16 v[92:95], v[146:149], v[204:207], v[92:95]
	v_mfma_f32_16x16x32_bf16 v[88:91], v[154:157], v[204:207], v[88:91]
	v_mfma_f32_16x16x32_bf16 v[76:79], v[146:149], v[212:215], v[76:79]
	v_mfma_f32_16x16x32_bf16 v[72:75], v[154:157], v[212:215], v[72:75]
	s_setprio 0
	s_setprio 1
	v_mfma_f32_16x16x32_bf16 v[116:119], v[158:161], v[178:181], v[116:119]
	v_mfma_f32_16x16x32_bf16 v[112:115], v[170:173], v[178:181], v[112:115]
	v_mfma_f32_16x16x32_bf16 v[100:103], v[158:161], v[192:195], v[100:103]
	v_mfma_f32_16x16x32_bf16 v[96:99], v[170:173], v[192:195], v[96:99]
	v_mfma_f32_16x16x32_bf16 v[84:87], v[158:161], v[200:203], v[84:87]
	v_mfma_f32_16x16x32_bf16 v[80:83], v[170:173], v[200:203], v[80:83]
	v_mfma_f32_16x16x32_bf16 v[68:71], v[158:161], v[208:211], v[68:71]
	v_mfma_f32_16x16x32_bf16 v[64:67], v[170:173], v[208:211], v[64:67]
	v_mfma_f32_16x16x32_bf16 v[116:119], v[166:169], v[182:185], v[116:119]
	v_mfma_f32_16x16x32_bf16 v[112:115], v[174:177], v[182:185], v[112:115]
	v_mfma_f32_16x16x32_bf16 v[100:103], v[166:169], v[196:199], v[100:103]
	v_mfma_f32_16x16x32_bf16 v[96:99], v[174:177], v[196:199], v[96:99]
	v_mfma_f32_16x16x32_bf16 v[84:87], v[166:169], v[204:207], v[84:87]
	v_mfma_f32_16x16x32_bf16 v[80:83], v[174:177], v[204:207], v[80:83]
	v_mfma_f32_16x16x32_bf16 v[68:71], v[166:169], v[212:215], v[68:71]
	v_mfma_f32_16x16x32_bf16 v[64:67], v[174:177], v[212:215], v[64:67]
	s_setprio 0
	s_barrier
; #define PG8_BAR __builtin_amdgcn_s_barrier()
;     ...
;         if constexpr (Epi::MIDHOOK) {
;             for (int t = 0; t < 4; t += 2) PG8_ITER(t);
;             E.mid(acc, cur, wr, wc, fr, fq);
;             for (int t = 4; t < nt; t += 2) PG8_ITER(t);
;         } else {
;             for (int t = 0; t < nt; t += 2) PG8_ITER(t);
;         }
;     ...
;         if constexpr (ALIGN_EPI) { if (wr == 0) PG8_BAR; }
;         if constexpr (!Epi::AFTER_DRAIN) { E(acc, cur, wr, wc, fr, fq); }
;         if (!has_next) break;
; #pragma unroll
;         for (int a = 0; a < 2; ++a)
; #pragma unroll
;             for (int b = 0; b < 2; ++b)
; #pragma unroll
;                 for (int m = 0; m < 4; ++m)
; #pragma unroll
;                     for (int n = 0; n < 2; ++n) acc[a][b][m][n] = (f32x4){0.f, 0.f, 0.f, 0.f};
;         cur = nxt; cA = nA; cB = nB; ++ui;
	s_or_b32 s47, s45, 0x80
	v_add_u32_e32 v162, s47, v133
	s_add_i32 s46, s46, s23
	ds_read_b128 v[178:181], v139 offset:49152
	ds_read_b128 v[182:185], v139 offset:50176
	ds_read_b128 v[192:195], v139 offset:51200
	ds_read_b128 v[196:199], v139 offset:52224
	ds_read_b128 v[200:203], v139 offset:53248
	ds_read_b128 v[204:207], v139 offset:54272
	ds_read_b128 v[208:211], v139 offset:55296
	ds_read_b128 v[212:215], v139 offset:56320
	s_mov_b32 m0, s46
	s_add_i32 s45, s45, 0xb0080
	global_load_lds_dwordx4 v162, s[14:15]
	v_add_u32_e32 v162, s47, v135
	s_add_i32 m0, s46, 0x2000
	s_add_i32 s46, s48, s23
	global_load_lds_dwordx4 v162, s[14:15]
	v_add_u32_e32 v162, s45, v133
	s_mov_b32 m0, s46
	s_nop 0
	global_load_lds_dwordx4 v162, s[14:15]
	v_add_u32_e32 v162, s45, v135
	s_add_i32 m0, s46, 0x2000
	s_nop 0
	global_load_lds_dwordx4 v162, s[14:15]
	v_add_u32_e32 v162, s44, v132
	s_mov_b32 m0, s30
	s_nop 0
	global_load_lds_dwordx4 v162, s[2:3]
	v_add_u32_e32 v162, s44, v134
	s_mov_b32 m0, s31
	s_nop 0
	global_load_lds_dwordx4 v162, s[2:3]
	s_waitcnt vmcnt(8)
	s_waitcnt lgkmcnt(0)
	s_barrier
	s_setprio 1
	s_waitcnt lgkmcnt(0)
	v_mfma_f32_16x16x32_bf16 v[60:63], v[142:145], v[178:181], v[60:63]
	v_mfma_f32_16x16x32_bf16 v[56:59], v[150:153], v[178:181], v[56:59]
	v_mfma_f32_16x16x32_bf16 v[44:47], v[142:145], v[192:195], v[44:47]
	v_mfma_f32_16x16x32_bf16 v[40:43], v[150:153], v[192:195], v[40:43]
	v_mfma_f32_16x16x32_bf16 v[28:31], v[142:145], v[200:203], v[28:31]
	v_mfma_f32_16x16x32_bf16 v[24:27], v[150:153], v[200:203], v[24:27]
	v_mfma_f32_16x16x32_bf16 v[12:15], v[142:145], v[208:211], v[12:15]
	v_mfma_f32_16x16x32_bf16 v[8:11], v[150:153], v[208:211], v[8:11]
	v_mfma_f32_16x16x32_bf16 v[60:63], v[146:149], v[182:185], v[60:63]
	v_mfma_f32_16x16x32_bf16 v[56:59], v[154:157], v[182:185], v[56:59]
	v_mfma_f32_16x16x32_bf16 v[44:47], v[146:149], v[196:199], v[44:47]
	v_mfma_f32_16x16x32_bf16 v[40:43], v[154:157], v[196:199], v[40:43]
	v_mfma_f32_16x16x32_bf16 v[28:31], v[146:149], v[204:207], v[28:31]
	v_mfma_f32_16x16x32_bf16 v[24:27], v[154:157], v[204:207], v[24:27]
	v_mfma_f32_16x16x32_bf16 v[12:15], v[146:149], v[212:215], v[12:15]
	v_mfma_f32_16x16x32_bf16 v[8:11], v[154:157], v[212:215], v[8:11]
	s_setprio 0
	s_setprio 1
	v_mfma_f32_16x16x32_bf16 v[52:55], v[158:161], v[178:181], v[52:55]
	v_mfma_f32_16x16x32_bf16 v[48:51], v[170:173], v[178:181], v[48:51]
	v_mfma_f32_16x16x32_bf16 v[36:39], v[158:161], v[192:195], v[36:39]
	v_mfma_f32_16x16x32_bf16 v[32:35], v[170:173], v[192:195], v[32:35]
	v_mfma_f32_16x16x32_bf16 v[20:23], v[158:161], v[200:203], v[20:23]
	v_mfma_f32_16x16x32_bf16 v[16:19], v[170:173], v[200:203], v[16:19]
	v_mfma_f32_16x16x32_bf16 v[4:7], v[158:161], v[208:211], v[4:7]
	v_mfma_f32_16x16x32_bf16 v[0:3], v[170:173], v[208:211], v[0:3]
	v_mfma_f32_16x16x32_bf16 v[52:55], v[166:169], v[182:185], v[52:55]
	v_mfma_f32_16x16x32_bf16 v[48:51], v[174:177], v[182:185], v[48:51]
	v_mfma_f32_16x16x32_bf16 v[36:39], v[166:169], v[196:199], v[36:39]
	v_mfma_f32_16x16x32_bf16 v[32:35], v[174:177], v[196:199], v[32:35]
	v_mfma_f32_16x16x32_bf16 v[20:23], v[166:169], v[204:207], v[20:23]
	v_mfma_f32_16x16x32_bf16 v[16:19], v[174:177], v[204:207], v[16:19]
	v_mfma_f32_16x16x32_bf16 v[4:7], v[166:169], v[212:215], v[4:7]
	v_mfma_f32_16x16x32_bf16 v[0:3], v[174:177], v[212:215], v[0:3]
	s_setprio 0
	s_add_i32 s42, s42, 2
	s_cmp_gt_u32 s42, 41
	s_mov_b32 s46, s43
	s_barrier
	s_cbranch_scc0 .LBB0_924
	s_andn2_b64 vcc, exec, s[4:5]
	s_cbranch_vccnz .LBB0_916
	v_mov_b32_e32 v0, 0
	s_mov_b32 s12, s36
	s_mov_b32 s19, s37
	s_mov_b32 s25, s17
	s_mov_b32 s26, s16
	s_mov_b32 s33, s38
	v_mov_b32_e32 v1, v0
	v_mov_b32_e32 v2, v0
	v_mov_b32_e32 v3, v0
	v_mov_b32_e32 v4, v0
	v_mov_b32_e32 v5, v0
	v_mov_b32_e32 v6, v0
	v_mov_b32_e32 v7, v0
	v_mov_b32_e32 v16, v0
	v_mov_b32_e32 v17, v0
	v_mov_b32_e32 v18, v0
	v_mov_b32_e32 v19, v0
	v_mov_b32_e32 v20, v0
	v_mov_b32_e32 v21, v0
	v_mov_b32_e32 v22, v0
	v_mov_b32_e32 v23, v0
	v_mov_b32_e32 v32, v0
	v_mov_b32_e32 v33, v0
	v_mov_b32_e32 v34, v0
	v_mov_b32_e32 v35, v0
	v_mov_b32_e32 v36, v0
	v_mov_b32_e32 v37, v0
	v_mov_b32_e32 v38, v0
	v_mov_b32_e32 v39, v0
	v_mov_b32_e32 v48, v0
	v_mov_b32_e32 v49, v0
	v_mov_b32_e32 v50, v0
	v_mov_b32_e32 v51, v0
	v_mov_b32_e32 v52, v0
	v_mov_b32_e32 v53, v0
	v_mov_b32_e32 v54, v0
	v_mov_b32_e32 v55, v0
	v_mov_b32_e32 v8, v0
	v_mov_b32_e32 v9, v0
	v_mov_b32_e32 v10, v0
	v_mov_b32_e32 v11, v0
	v_mov_b32_e32 v12, v0
	v_mov_b32_e32 v13, v0
	v_mov_b32_e32 v14, v0
	v_mov_b32_e32 v15, v0
	v_mov_b32_e32 v24, v0
	v_mov_b32_e32 v25, v0
	v_mov_b32_e32 v26, v0
	v_mov_b32_e32 v27, v0
	v_mov_b32_e32 v28, v0
	v_mov_b32_e32 v29, v0
	v_mov_b32_e32 v30, v0
	v_mov_b32_e32 v31, v0
	v_mov_b32_e32 v40, v0
	v_mov_b32_e32 v41, v0
	v_mov_b32_e32 v42, v0
	v_mov_b32_e32 v43, v0
	v_mov_b32_e32 v44, v0
	v_mov_b32_e32 v45, v0
	v_mov_b32_e32 v46, v0
	v_mov_b32_e32 v47, v0
	v_mov_b32_e32 v56, v0
	v_mov_b32_e32 v57, v0
	v_mov_b32_e32 v58, v0
	v_mov_b32_e32 v59, v0
	v_mov_b32_e32 v60, v0
	v_mov_b32_e32 v61, v0
	v_mov_b32_e32 v62, v0
	v_mov_b32_e32 v63, v0
	v_mov_b32_e32 v64, v0
	v_mov_b32_e32 v65, v0
	v_mov_b32_e32 v66, v0
	v_mov_b32_e32 v67, v0
	v_mov_b32_e32 v68, v0
	v_mov_b32_e32 v69, v0
	v_mov_b32_e32 v70, v0
	v_mov_b32_e32 v71, v0
	v_mov_b32_e32 v80, v0
	v_mov_b32_e32 v81, v0
	v_mov_b32_e32 v82, v0
	v_mov_b32_e32 v83, v0
	v_mov_b32_e32 v84, v0
	v_mov_b32_e32 v85, v0
	v_mov_b32_e32 v86, v0
	v_mov_b32_e32 v87, v0
	v_mov_b32_e32 v96, v0
	v_mov_b32_e32 v97, v0
	v_mov_b32_e32 v98, v0
	v_mov_b32_e32 v99, v0
	v_mov_b32_e32 v100, v0
	v_mov_b32_e32 v101, v0
	v_mov_b32_e32 v102, v0
	v_mov_b32_e32 v103, v0
	v_mov_b32_e32 v112, v0
	v_mov_b32_e32 v113, v0
	v_mov_b32_e32 v114, v0
	v_mov_b32_e32 v115, v0
	v_mov_b32_e32 v116, v0
	v_mov_b32_e32 v117, v0
	v_mov_b32_e32 v118, v0
	v_mov_b32_e32 v119, v0
	v_mov_b32_e32 v72, v0
	v_mov_b32_e32 v73, v0
	v_mov_b32_e32 v74, v0
	v_mov_b32_e32 v75, v0
	v_mov_b32_e32 v76, v0
	v_mov_b32_e32 v77, v0
	v_mov_b32_e32 v78, v0
	v_mov_b32_e32 v79, v0
	v_mov_b32_e32 v88, v0
	v_mov_b32_e32 v89, v0
	v_mov_b32_e32 v90, v0
	v_mov_b32_e32 v91, v0
	v_mov_b32_e32 v92, v0
	v_mov_b32_e32 v93, v0
	v_mov_b32_e32 v94, v0
	v_mov_b32_e32 v95, v0
	v_mov_b32_e32 v104, v0
	v_mov_b32_e32 v105, v0
	v_mov_b32_e32 v106, v0
	v_mov_b32_e32 v107, v0
	v_mov_b32_e32 v108, v0
	v_mov_b32_e32 v109, v0
	v_mov_b32_e32 v110, v0
	v_mov_b32_e32 v111, v0
	v_mov_b32_e32 v120, v0
	v_mov_b32_e32 v121, v0
	v_mov_b32_e32 v122, v0
	v_mov_b32_e32 v123, v0
	v_mov_b32_e32 v124, v0
	v_mov_b32_e32 v125, v0
	v_mov_b32_e32 v126, v0
	v_mov_b32_e32 v127, v0
	s_branch .LBB0_916
